# ZERO64: accumulator zeroing before each GEMM / attention tile loop with v_mov_b64 pairs instead of single v_mov_b32 copies (386 pairs), on SO7
# baseline (speedup 1.0000x reference)
.LBB0_103:
	s_or_saveexec_b64 s[6:7], s[6:7]
	v_and_b32_e32 v1, 63, v0
	s_xor_b64 exec, exec, s[6:7]
	v_lshlrev_b32_e32 v2, 1, v0
	v_lshrrev_b32_e32 v4, 2, v0
	v_and_b32_e32 v2, 24, v2
	v_and_b32_e32 v10, 4, v4
	v_and_b32_e32 v3, 0xffffffe3, v3
	v_or3_b32 v2, v2, v3, v10
	s_or_b64 exec, exec, s[6:7]
	s_and_b32 s0, s0, 0x3fff0
	s_sub_i32 s0, s58, s0
	v_lshrrev_b32_e32 v11, 6, v0
	v_lshl_or_b32 v3, s0, 6, v11
	v_mul_i32_i24_e32 v4, 0x2100, v3
	v_ashrrev_i32_e32 v5, 31, v4
	s_waitcnt lgkmcnt(0)
	v_lshl_add_u64 v[4:5], v[4:5], 2, s[4:5]
	v_ashrrev_i32_e32 v3, 31, v2
	v_lshl_add_u64 v[2:3], v[2:3], 2, v[4:5]
	s_mov_b32 s0, 0x42000
	v_add_co_u32_e32 v6, vcc, s0, v2
	s_mov_b32 s0, 0x84000
	s_nop 0
	v_addc_co_u32_e32 v7, vcc, 0, v3, vcc
	v_add_co_u32_e32 v8, vcc, s0, v2
	s_mov_b32 s0, 0xc6000
	s_nop 0
	v_addc_co_u32_e32 v9, vcc, 0, v3, vcc
	v_add_co_u32_e32 v20, vcc, s0, v2
	s_mov_b32 s0, 0x108000
	s_nop 0
	v_addc_co_u32_e32 v21, vcc, 0, v3, vcc
	v_add_co_u32_e32 v22, vcc, s0, v2
	s_mov_b32 s0, 0x14a000
	s_nop 0
	v_addc_co_u32_e32 v23, vcc, 0, v3, vcc
	v_add_co_u32_e32 v24, vcc, s0, v2
	s_mov_b32 s0, 0x18c000
	s_nop 0
	v_addc_co_u32_e32 v25, vcc, 0, v3, vcc
	v_add_co_u32_e32 v26, vcc, s0, v2
	s_mov_b32 s0, 0x1ce000
	s_nop 0
	v_addc_co_u32_e32 v27, vcc, 0, v3, vcc
	v_add_co_u32_e32 v28, vcc, s0, v2
	s_movk_i32 s0, 0x1100
	s_nop 0
	v_addc_co_u32_e32 v29, vcc, 0, v3, vcc
	global_load_dword v17, v[2:3], off
	global_load_dword v16, v[6:7], off
	global_load_dword v15, v[8:9], off
	global_load_dword v14, v[20:21], off
	global_load_dword v13, v[22:23], off
	global_load_dword v5, v[24:25], off
	global_load_dword v4, v[26:27], off
	global_load_dword v18, v[28:29], off
	v_and_b32_e32 v2, 3, v0
	s_add_u32 s6, s10, 0x800000
	v_or3_b32 v6, v2, v10, s0
	v_lshlrev_b32_e32 v2, 3, v0
	s_addc_u32 s7, s11, 0
	v_lshrrev_b32_e32 v8, 3, v0
	v_and_b32_e32 v2, 56, v2
	s_add_i32 s3, s58, s73
	v_lshlrev_b32_e32 v19, 1, v0
	v_mul_u32_u24_e32 v3, 0x104, v2
	v_lshlrev_b32_e32 v9, 2, v8
	s_mul_i32 s3, s3, 0x84000
	s_movk_i32 s2, 0x2100
	v_lshl_add_u32 v12, v1, 2, 0
	v_add3_u32 v9, 0, v3, v9
	v_mov_b32_e32 v3, 0
	v_mul_u32_u24_e32 v20, 0x104, v11
	v_and_or_b32 v10, v19, 24, v10
	v_mov_b32_e32 v19, s3
	v_and_b32_e32 v7, 31, v0
	s_lshl_b32 s0, s58, 6
	s_lshl_b32 s1, s73, 6
	v_mad_u32_u24 v11, v11, s2, v19
	s_mul_i32 s2, s73, 0x84000
	v_add_u32_e32 v12, v12, v20
	s_movk_i32 s3, 0x10ff
	s_movk_i32 s18, 0x7ff
	s_movk_i32 s19, 0x700
	s_movk_i32 s20, 0xffe3
	s_movk_i32 s21, 0x7fff
	s_mov_b32 s22, 0xffff0000
	v_lshlrev_b32_e32 v2, 1, v2
	s_mov_b32 s24, s58
	v_mov_b32_e32 v19, v3
	v_mov_b64 v[20:21], 0
	v_mov_b64 v[22:23], 0
	v_mov_b64 v[24:25], 0
	v_mov_b32_e32 v26, v3
	s_branch .LBB0_108

.LBB0_117:
	s_abs_i32 s0, s73
	v_cvt_f32_u32_e32 v1, s0
	s_add_i32 s1, s58, 0xfffff7c0
	s_ashr_i32 s2, s1, 31
	s_abs_i32 s3, s1
	v_rcp_iflag_f32_e32 v1, v1
	s_sub_i32 s1, 0, s0
	v_mul_f32_e32 v1, 0x4f7ffffe, v1
	v_cvt_u32_f32_e32 v1, v1
	s_nop 0
	v_readfirstlane_b32 s4, v1
	s_mul_i32 s1, s1, s4
	s_mul_hi_u32 s1, s4, s1
	s_add_i32 s1, s4, s1
	s_mul_hi_u32 s4, s3, s1
	s_mul_i32 s4, s4, s0
	s_sub_i32 s3, s3, s4
	s_sub_i32 s4, s3, s0
	s_cmp_ge_u32 s3, s0
	s_cselect_b32 s3, s4, s3
	s_sub_i32 s4, s3, s0
	s_cmp_ge_u32 s3, s0
	s_cselect_b32 s3, s4, s3
	s_xor_b32 s3, s3, s2
	s_sub_i32 s2, s3, s2
	s_add_i32 s2, s2, s73
	s_ashr_i32 s3, s2, 31
	s_abs_i32 s2, s2
	s_mul_hi_u32 s4, s2, s1
	s_mul_i32 s4, s4, s0
	s_sub_i32 s2, s2, s4
	s_sub_i32 s4, s2, s0
	s_cmp_ge_u32 s2, s0
	s_cselect_b32 s2, s4, s2
	s_sub_i32 s4, s2, s0
	s_cmp_ge_u32 s2, s0
	s_cselect_b32 s2, s4, s2
	s_xor_b32 s2, s2, s3
	s_sub_i32 s15, s2, s3
	s_cmpk_gt_i32 s15, 0x1ff
	s_cbranch_scc1 .LBB0_122
	s_waitcnt lgkmcnt(0)
	s_add_u32 s6, s10, 0x1900000
	s_addc_u32 s7, s11, 0
	s_ashr_i32 s2, s15, 31
	s_lshr_b32 s2, s2, 27
	s_add_i32 s2, s15, s2
	s_load_dwordx2 s[4:5], s[60:61], 0x60
	s_and_b32 s3, s2, 0x3ffffe0
	s_sub_i32 s3, s15, s3
	v_lshrrev_b32_e32 v16, 6, v0
	s_lshl_b32 s2, s2, 1
	v_lshl_or_b32 v4, s3, 6, v16
	s_movk_i32 s12, 0xffc0
	v_mov_b32_e32 v1, s2
	v_ashrrev_i32_e32 v5, 31, v4
	v_bfi_b32 v2, s12, v1, v0
	v_lshlrev_b64 v[4:5], 12, v[4:5]
	s_waitcnt lgkmcnt(0)
	v_lshl_add_u64 v[4:5], s[4:5], 0, v[4:5]
	v_ashrrev_i32_e32 v3, 31, v2
	v_lshl_add_u64 v[2:3], v[2:3], 2, v[4:5]
	s_mov_b32 s2, 0x8000
	v_add_co_u32_e32 v4, vcc, s2, v2
	s_mov_b32 s3, 0x10000
	s_nop 0
	v_addc_co_u32_e32 v5, vcc, 0, v3, vcc
	v_add_co_u32_e32 v6, vcc, s3, v2
	s_mov_b32 s14, 0x18000
	s_nop 0
	v_addc_co_u32_e32 v7, vcc, 0, v3, vcc
	v_add_co_u32_e32 v8, vcc, s14, v2
	s_mov_b32 s12, 0x20000
	s_nop 0
	v_addc_co_u32_e32 v9, vcc, 0, v3, vcc
	v_add_co_u32_e32 v10, vcc, s12, v2
	s_mov_b32 s12, 0x28000
	s_nop 0
	v_addc_co_u32_e32 v11, vcc, 0, v3, vcc
	v_add_co_u32_e32 v12, vcc, s12, v2
	s_mov_b32 s12, 0x30000
	s_nop 0
	v_addc_co_u32_e32 v13, vcc, 0, v3, vcc
	v_add_co_u32_e32 v14, vcc, s12, v2
	s_mov_b32 s12, 0x38000
	s_nop 0
	v_addc_co_u32_e32 v15, vcc, 0, v3, vcc
	v_add_co_u32_e32 v26, vcc, s12, v2
	v_and_b32_e32 v1, 63, v0
	s_nop 0
	v_addc_co_u32_e32 v27, vcc, 0, v3, vcc
	global_load_dword v17, v[2:3], off
	global_load_dword v18, v[4:5], off
	global_load_dword v19, v[6:7], off
	global_load_dword v20, v[8:9], off
	global_load_dword v21, v[10:11], off
	global_load_dword v22, v[12:13], off
	global_load_dword v23, v[14:15], off
	global_load_dword v24, v[26:27], off
	v_lshlrev_b32_e32 v2, 3, v0
	v_lshrrev_b32_e32 v4, 3, v0
	v_and_b32_e32 v2, 56, v2
	v_mul_u32_u24_e32 v3, 0x104, v2
	v_lshlrev_b32_e32 v5, 2, v4
	v_lshl_add_u32 v6, v1, 2, 0
	v_add3_u32 v8, 0, v3, v5
	v_mov_b32_e32 v3, 0
	v_mul_u32_u24_e32 v7, 0x104, v16
	s_lshl_b32 s17, s73, 6
	s_lshl_b32 s16, s15, 6
	v_or_b32_e32 v5, s17, v16
	v_add_u32_e32 v6, v6, v7
	s_movk_i32 s18, 0x7fff
	s_mov_b32 s19, 0xffff0000
	v_lshlrev_b32_e32 v2, 1, v2
	v_add_u32_e32 v7, 0x8000, v8
	v_add_u32_e32 v8, 0x8400, v8
	v_mov_b32_e32 v9, v3
	v_mov_b64 v[10:11], 0
	v_mov_b64 v[12:13], 0
	v_mov_b64 v[14:15], 0
	v_mov_b32_e32 v16, v3
	s_branch .LBB0_120

.LBB0_124:
.LBB0_125:
	s_waitcnt lgkmcnt(0)
	s_add_u32 s6, s10, 0x400000
	s_addc_u32 s7, s11, 0
	s_ashr_i32 s0, s3, 31
	s_lshr_b32 s0, s0, 27
	s_add_i32 s0, s3, s0
	s_and_b32 s1, s0, 0x3ffffe0
	s_lshl_b32 s0, s0, 1
	s_load_dwordx2 s[4:5], s[60:61], 0xf0
	s_movk_i32 s2, 0xffc0
	v_mov_b32_e32 v1, s0
	s_sub_i32 s1, s3, s1
	v_bfi_b32 v2, s2, v1, v0
	v_lshrrev_b32_e32 v1, 6, v0
	v_lshl_or_b32 v4, s1, 6, v1
	v_ashrrev_i32_e32 v5, 31, v4
	v_lshlrev_b64 v[4:5], 12, v[4:5]
	s_waitcnt lgkmcnt(0)
	v_lshl_add_u64 v[4:5], s[4:5], 0, v[4:5]
	v_ashrrev_i32_e32 v3, 31, v2
	v_lshl_add_u64 v[2:3], v[2:3], 2, v[4:5]
	s_mov_b32 s0, 0x8000
	v_add_co_u32_e32 v4, vcc, s0, v2
	s_mov_b32 s1, 0x10000
	s_nop 0
	v_addc_co_u32_e32 v5, vcc, 0, v3, vcc
	v_add_co_u32_e32 v6, vcc, s1, v2
	s_mov_b32 s2, 0x18000
	s_nop 0
	v_addc_co_u32_e32 v7, vcc, 0, v3, vcc
	v_add_co_u32_e32 v8, vcc, s2, v2
	s_mov_b32 s12, 0x20000
	s_nop 0
	v_addc_co_u32_e32 v9, vcc, 0, v3, vcc
	v_add_co_u32_e32 v10, vcc, s12, v2
	s_mov_b32 s12, 0x28000
	s_nop 0
	v_addc_co_u32_e32 v11, vcc, 0, v3, vcc
	v_add_co_u32_e32 v12, vcc, s12, v2
	s_mov_b32 s12, 0x30000
	s_nop 0
	v_addc_co_u32_e32 v13, vcc, 0, v3, vcc
	v_add_co_u32_e32 v14, vcc, s12, v2
	s_mov_b32 s12, 0x38000
	s_nop 0
	v_addc_co_u32_e32 v15, vcc, 0, v3, vcc
	v_add_co_u32_e32 v16, vcc, s12, v2
	s_lshl_b32 s15, s73, 6
	s_nop 0
	v_addc_co_u32_e32 v17, vcc, 0, v3, vcc
	global_load_dword v18, v[2:3], off
	global_load_dword v19, v[4:5], off
	global_load_dword v20, v[6:7], off
	global_load_dword v21, v[8:9], off
	global_load_dword v22, v[10:11], off
	global_load_dword v23, v[12:13], off
	global_load_dword v24, v[14:15], off
	global_load_dword v25, v[16:17], off
	v_lshlrev_b32_e32 v2, 3, v0
	v_lshrrev_b32_e32 v5, 3, v0
	v_and_b32_e32 v2, 56, v2
	v_and_b32_e32 v4, 63, v0
	v_mul_u32_u24_e32 v3, 0x104, v2
	v_lshlrev_b32_e32 v6, 2, v5
	v_lshl_add_u32 v7, v4, 2, 0
	v_add3_u32 v9, 0, v3, v6
	v_mov_b32_e32 v3, 0
	v_mul_u32_u24_e32 v8, 0x104, v1
	s_lshl_b32 s14, s3, 6
	v_or_b32_e32 v6, s15, v1
	v_add_u32_e32 v7, v7, v8
	s_movk_i32 s16, 0x7fff
	s_mov_b32 s17, 0xffff0000
	v_lshlrev_b32_e32 v2, 1, v2
	v_add_u32_e32 v8, 0x8000, v9
	v_add_u32_e32 v9, 0x8400, v9
	v_mov_b64 v[10:11], 0
	v_mov_b64 v[12:13], 0
	v_mov_b64 v[14:15], 0
	v_mov_b64 v[16:17], 0
	s_branch .LBB0_127

.LBB0_212:
	s_ashr_i32 s27, s26, 31
	s_lshl_b64 s[30:31], s[26:27], 19
	s_ashr_i32 s25, s24, 31
	v_lshl_add_u64 v[148:149], v[130:131], 0, s[30:31]
	s_lshl_b64 s[30:31], s[24:25], 19
	v_lshl_add_u64 v[150:151], v[132:133], 0, s[30:31]
	v_cndmask_b32_e64 v152, v2, v150, s[4:5]
	v_lshl_add_u64 v[156:157], v[2:3], 0, s[20:21]
	v_mov_b32_e32 v2, 0
	v_cndmask_b32_e64 v1, v5, v149, s[4:5]
	v_cndmask_b32_e64 v138, v4, v148, s[4:5]
	v_cndmask_b32_e64 v153, v3, v151, s[4:5]
	v_lshl_add_u64 v[154:155], v[4:5], 0, s[16:17]
	s_mov_b32 s7, -2
	v_mov_b32_e32 v3, v2
	v_mov_b64 v[4:5], 0
	v_mov_b64 v[6:7], 0
	v_mov_b64 v[8:9], 0
	v_mov_b64 v[18:19], 0
	v_mov_b64 v[20:21], 0
	v_mov_b64 v[22:23], 0
	v_mov_b64 v[24:25], 0
	v_mov_b64 v[34:35], 0
	v_mov_b64 v[36:37], 0
	v_mov_b64 v[38:39], 0
	v_mov_b64 v[40:41], 0
	v_mov_b64 v[50:51], 0
	v_mov_b64 v[52:53], 0
	v_mov_b64 v[54:55], 0
	v_mov_b64 v[56:57], 0
	v_mov_b64 v[10:11], 0
	v_mov_b64 v[12:13], 0
	v_mov_b64 v[14:15], 0
	v_mov_b64 v[16:17], 0
	v_mov_b64 v[26:27], 0
	v_mov_b64 v[28:29], 0
	v_mov_b64 v[30:31], 0
	v_mov_b64 v[32:33], 0
	v_mov_b64 v[42:43], 0
	v_mov_b64 v[44:45], 0
	v_mov_b64 v[46:47], 0
	v_mov_b64 v[48:49], 0
	v_mov_b64 v[58:59], 0
	v_mov_b64 v[60:61], 0
	v_mov_b64 v[62:63], 0
	v_mov_b64 v[64:65], 0
	v_mov_b64 v[66:67], 0
	v_mov_b64 v[68:69], 0
	v_mov_b64 v[70:71], 0
	v_mov_b64 v[72:73], 0
	v_mov_b64 v[82:83], 0
	v_mov_b64 v[84:85], 0
	v_mov_b64 v[86:87], 0
	v_mov_b64 v[88:89], 0
	v_mov_b64 v[98:99], 0
	v_mov_b64 v[100:101], 0
	v_mov_b64 v[102:103], 0
	v_mov_b64 v[104:105], 0
	v_mov_b64 v[114:115], 0
	v_mov_b64 v[116:117], 0
	v_mov_b64 v[118:119], 0
	v_mov_b64 v[120:121], 0
	v_mov_b64 v[74:75], 0
	v_mov_b64 v[76:77], 0
	v_mov_b64 v[78:79], 0
	v_mov_b64 v[80:81], 0
	v_mov_b64 v[90:91], 0
	v_mov_b64 v[92:93], 0
	v_mov_b64 v[94:95], 0
	v_mov_b64 v[96:97], 0
	v_mov_b64 v[106:107], 0
	v_mov_b64 v[108:109], 0
	v_mov_b64 v[110:111], 0
	v_mov_b64 v[112:113], 0
	v_mov_b64 v[122:123], 0
	v_mov_b64 v[124:125], 0
	v_mov_b64 v[126:127], 0
	v_mov_b64 v[128:129], 0

.LBB0_355:
	s_or_b64 exec, exec, s[10:11]
	s_and_b32 s1, s4, 1
	s_and_b64 s[8:9], s[8:9], exec
	s_cselect_b32 s2, s1, -1
	s_lshr_b32 s1, s0, 6
	s_ashr_i32 s80, s3, 5
	s_cmpk_lt_u32 s0, 0x80
	v_readlane_b32 s8, v255, 49
	s_cselect_b64 s[10:11], -1, 0
	v_readlane_b32 s9, v255, 50
	v_writelane_b32 v255, s10, 52
	s_and_b64 s[8:9], s[10:11], s[8:9]
	s_cmp_lg_u32 s2, 1
	v_writelane_b32 v255, s11, 53
	s_cselect_b64 s[10:11], -1, 0
	v_writelane_b32 v255, s10, 54
	s_and_b64 s[8:9], s[10:11], s[8:9]
	v_mov_b32_e32 v2, 0
	v_writelane_b32 v255, s11, 55
	s_and_b64 vcc, exec, s[8:9]
	v_lshlrev_b32_e32 v126, 2, v104
	v_mov_b32_e32 v3, v2
	v_mov_b64 v[4:5], 0
	v_mov_b64 v[6:7], 0
	v_mov_b64 v[8:9], 0
	v_mov_b64 v[10:11], 0
	v_mov_b64 v[12:13], 0
	v_mov_b64 v[14:15], 0
	v_mov_b64 v[16:17], 0
	v_mov_b64 v[18:19], 0
	v_mov_b64 v[20:21], 0
	v_mov_b64 v[22:23], 0
	v_mov_b64 v[24:25], 0
	v_mov_b64 v[26:27], 0
	v_mov_b64 v[28:29], 0
	v_mov_b64 v[30:31], 0
	v_mov_b64 v[32:33], 0
	s_cbranch_vccz .LBB0_357
	v_readlane_b32 s8, v255, 11
	s_lshl_b32 s3, s30, 3
	v_readlane_b32 s9, v255, 12
	s_load_dwordx2 s[8:9], s[8:9], s3 offset:0x10
	s_lshl_b32 s3, s80, 4
	s_or_b32 s10, s3, s56
	s_ashr_i32 s11, s10, 31
	s_lshl_b64 s[10:11], s[10:11], 6
	s_lshl_b32 s3, s1, 5
	s_or_b32 s3, s10, s3
	v_mov_b32_e32 v3, s11
	v_or_b32_e32 v2, s3, v102
	v_lshlrev_b64 v[2:3], 8, v[2:3]
	s_waitcnt lgkmcnt(0)
	v_lshl_add_u64 v[2:3], s[8:9], 0, v[2:3]
	v_mov_b32_e32 v127, v107
	v_lshl_add_u64 v[30:31], v[2:3], 0, v[126:127]
	global_load_dwordx4 v[2:5], v[30:31], off
	global_load_dwordx4 v[6:9], v[30:31], off offset:32
	global_load_dwordx4 v[10:13], v[30:31], off offset:64
	global_load_dwordx4 v[14:17], v[30:31], off offset:96
	global_load_dwordx4 v[18:21], v[30:31], off offset:128
	global_load_dwordx4 v[22:25], v[30:31], off offset:160
	global_load_dwordx4 v[26:29], v[30:31], off offset:192
	s_nop 0
	global_load_dwordx4 v[30:33], v[30:31], off offset:224

.LBB0_436:
	s_waitcnt vmcnt(0)
	s_or_b64 s[10:11], s[82:83], s[56:57]
	s_and_b64 vcc, exec, s[10:11]
	s_waitcnt lgkmcnt(0)
	s_barrier
	s_cbranch_vccnz .LBB0_438
	s_lshl_b32 s15, s49, 6
	s_sub_i32 s16, s63, s73
	s_add_i32 s17, s15, s0
	s_sub_i32 s18, s71, s17
	s_add_i32 s14, s15, s60
	s_sub_i32 s31, s71, s14
	s_and_b64 s[10:11], s[8:9], exec
	s_cselect_b32 s16, s15, s16
	s_cselect_b32 s17, s17, s18
	s_cselect_b32 s14, s14, s31
	v_lshrrev_b32_e32 v136, 3, v1
	v_and_b32_e32 v137, 7, v1
	v_lshlrev_b32_e32 v143, 4, v1
	v_mov_b64 v[144:145], 0
	v_mov_b64 v[146:147], 0
	v_add_u32_e32 v143, 0x22f00, v143
	v_lshlrev_b32_e32 v138, 4, v137
	v_add_u32_e32 v139, s17, v136
	v_add_u32_e32 v140, s14, v136
	ds_write_b128 v143, v[144:147]
	v_subrev_u32_e32 v98, s16, v139
	v_subrev_u32_e32 v99, s16, v140
	v_cmp_lt_i32_e32 vcc, 0, v139
	v_mad_u32_u24 v98, v98, s58, v138
	v_mad_u32_u24 v99, v99, s58, v138
	v_mov_b32_e32 v141, 0x1a580
	v_mov_b32_e32 v142, 0x1a080
	v_cndmask_b32_e32 v100, v141, v98, vcc
	v_cmp_gt_i32_e32 vcc, s33, v139
	v_lshlrev_b32_e32 v148, 5, v137
	v_add_u32_e32 v148, 0x22000, v148
	v_cndmask_b32_e32 v101, v142, v98, vcc
	v_cmp_lt_i32_e32 vcc, 0, v140
	ds_read_b128 v[168:171], v100 offset:35200
	ds_read_b128 v[172:175], v98 offset:35840
	ds_read_b128 v[176:179], v101 offset:36480
	ds_read_b128 v[192:195], v148 offset:768
	ds_read_b128 v[196:199], v148 offset:784
	v_cndmask_b32_e32 v220, v141, v99, vcc
	v_cmp_gt_i32_e32 vcc, s33, v140
	ds_read_b128 v[200:203], v148 offset:1024
	ds_read_b128 v[204:207], v148 offset:1040
	v_sub_u32_e32 v149, 7, v136
	v_cndmask_b32_e32 v221, v142, v99, vcc
	ds_read_b128 v[180:183], v100 offset:35328
	ds_read_b128 v[184:187], v98 offset:35968
	ds_read_b128 v[188:191], v101 offset:36608
	v_cndmask_b32_e64 v149, v149, v136, s[8:9]
	v_lshl_add_u32 v149, v149, 7, v138
	v_add_u32_e32 v222, s34, v149
	v_add_u32_e32 v223, s61, v149
	v_lshlrev_b32_e32 v224, 4, v1
	v_add_u32_e32 v224, 0x24000, v224
	s_waitcnt lgkmcnt(7)
	v_lshlrev_b32_e32 v136, 16, v168
	v_lshlrev_b32_e32 v138, 16, v176
	v_and_b32_e32 v137, 0xffff0000, v168
	v_lshlrev_b32_e32 v140, 16, v172
	v_and_b32_e32 v139, 0xffff0000, v176
	v_lshlrev_b32_e32 v142, 16, v169
	v_add_f32_e32 v136, v138, v136
	v_and_b32_e32 v141, 0xffff0000, v172
	v_lshlrev_b32_e32 v144, 16, v177
	v_and_b32_e32 v143, 0xffff0000, v169
	v_fma_f32 v136, v136, 0.5, -v140
	v_add_f32_e32 v137, v139, v137
	v_lshlrev_b32_e32 v146, 16, v173
	v_and_b32_e32 v145, 0xffff0000, v177
	v_lshlrev_b32_e32 v148, 16, v170
	s_waitcnt lgkmcnt(5)
	v_fmac_f32_e32 v140, v192, v136
	v_fma_f32 v137, v137, 0.5, -v141
	v_add_f32_e32 v142, v144, v142
	v_and_b32_e32 v147, 0xffff0000, v173
	v_lshlrev_b32_e32 v150, 16, v178
	v_and_b32_e32 v149, 0xffff0000, v170
	v_mul_f32_e32 v140, 0x4038aa3b, v140
	v_fmac_f32_e32 v141, v193, v137
	v_fma_f32 v142, v142, 0.5, -v146
	v_add_f32_e32 v143, v145, v143
	v_lshlrev_b32_e32 v152, 16, v174
	v_and_b32_e32 v151, 0xffff0000, v178
	v_lshlrev_b32_e32 v154, 16, v171
	v_exp_f32_e32 v140, v140
	v_mul_f32_e32 v141, 0x4038aa3b, v141
	v_fmac_f32_e32 v146, v194, v142
	v_fma_f32 v143, v143, 0.5, -v147
	v_add_f32_e32 v148, v150, v148
	v_and_b32_e32 v153, 0xffff0000, v174
	v_lshlrev_b32_e32 v156, 16, v179
	v_and_b32_e32 v155, 0xffff0000, v171
	v_add_f32_e32 v140, 1.0, v140
	v_exp_f32_e32 v141, v141
	v_mul_f32_e32 v146, 0x4038aa3b, v146
	v_fmac_f32_e32 v147, v195, v143
	v_fma_f32 v148, v148, 0.5, -v152
	v_add_f32_e32 v149, v151, v149
	v_lshlrev_b32_e32 v158, 16, v175
	v_and_b32_e32 v157, 0xffff0000, v179
	v_rcp_f32_e32 v140, v140
	v_add_f32_e32 v141, 1.0, v141
	v_exp_f32_e32 v146, v146
	v_mul_f32_e32 v147, 0x4038aa3b, v147
	v_fmac_f32_e32 v152, v196, v148
	v_fma_f32 v149, v149, 0.5, -v153
	v_add_f32_e32 v154, v156, v154
	v_and_b32_e32 v159, 0xffff0000, v175
	ds_read_b128 v[168:171], v220 offset:35200
	ds_read_b128 v[172:175], v99 offset:35840
	ds_read_b128 v[176:179], v221 offset:36480
	v_fma_f32 v140, -v140, 2.0, 1.0
	v_rcp_f32_e32 v141, v141
	v_add_f32_e32 v146, 1.0, v146
	v_exp_f32_e32 v147, v147
	v_mul_f32_e32 v152, 0x4038aa3b, v152
	v_fmac_f32_e32 v153, v197, v149
	v_fma_f32 v154, v154, 0.5, -v158
	v_add_f32_e32 v155, v157, v155
	v_fma_f32 v141, -v141, 2.0, 1.0
	v_rcp_f32_e32 v146, v146
	v_add_f32_e32 v147, 1.0, v147
	v_exp_f32_e32 v152, v152
	v_mul_f32_e32 v153, 0x4038aa3b, v153
	v_fmac_f32_e32 v158, v198, v154
	v_fma_f32 v155, v155, 0.5, -v159
	s_waitcnt lgkmcnt(3)
	v_lshlrev_b32_e32 v136, 16, v180
	v_cvt_pk_bf16_f32 v160, v140, v141
	v_fma_f32 v146, -v146, 2.0, 1.0
	v_rcp_f32_e32 v147, v147
	v_add_f32_e32 v152, 1.0, v152
	v_exp_f32_e32 v153, v153
	v_mul_f32_e32 v158, 0x4038aa3b, v158
	v_fmac_f32_e32 v159, v199, v155
	v_lshlrev_b32_e32 v138, 16, v188
	v_and_b32_e32 v137, 0xffff0000, v180
	v_fma_f32 v147, -v147, 2.0, 1.0
	v_rcp_f32_e32 v152, v152
	v_add_f32_e32 v153, 1.0, v153
	v_exp_f32_e32 v158, v158
	v_mul_f32_e32 v159, 0x4038aa3b, v159
	v_lshlrev_b32_e32 v140, 16, v184
	v_and_b32_e32 v139, 0xffff0000, v188
	v_lshlrev_b32_e32 v142, 16, v181
	v_cvt_pk_bf16_f32 v161, v146, v147
	v_fma_f32 v152, -v152, 2.0, 1.0
	v_rcp_f32_e32 v153, v153
	v_add_f32_e32 v158, 1.0, v158
	v_exp_f32_e32 v159, v159
	v_add_f32_e32 v136, v138, v136
	v_and_b32_e32 v141, 0xffff0000, v184
	v_lshlrev_b32_e32 v144, 16, v189
	v_and_b32_e32 v143, 0xffff0000, v181
	v_fma_f32 v153, -v153, 2.0, 1.0
	v_rcp_f32_e32 v158, v158
	v_add_f32_e32 v159, 1.0, v159
	v_fma_f32 v136, v136, 0.5, -v140
	v_add_f32_e32 v137, v139, v137
	v_lshlrev_b32_e32 v146, 16, v185
	v_and_b32_e32 v145, 0xffff0000, v189
	v_lshlrev_b32_e32 v148, 16, v182
	v_cvt_pk_bf16_f32 v162, v152, v153
	v_fma_f32 v158, -v158, 2.0, 1.0
	v_rcp_f32_e32 v159, v159
	v_fmac_f32_e32 v140, v200, v136
	v_fma_f32 v137, v137, 0.5, -v141
	v_add_f32_e32 v142, v144, v142
	v_and_b32_e32 v147, 0xffff0000, v185
	v_lshlrev_b32_e32 v150, 16, v190
	v_and_b32_e32 v149, 0xffff0000, v182
	v_fma_f32 v159, -v159, 2.0, 1.0
	v_fmac_f32_e32 v141, v201, v137
	v_fma_f32 v142, v142, 0.5, -v146
	v_add_f32_e32 v143, v145, v143
	v_lshlrev_b32_e32 v152, 16, v186
	v_and_b32_e32 v151, 0xffff0000, v190
	v_lshlrev_b32_e32 v154, 16, v183
	v_cvt_pk_bf16_f32 v163, v158, v159
	ds_write_b128 v222, v[160:163] offset:16384
	s_waitcnt lgkmcnt(1)
	v_lshlrev_b32_e32 v136, 16, v168
	v_cvt_pk_bf16_f32 v216, v140, v141
	v_fmac_f32_e32 v146, v202, v142
	v_fma_f32 v143, v143, 0.5, -v147
	v_add_f32_e32 v148, v150, v148
	v_and_b32_e32 v153, 0xffff0000, v186
	v_lshlrev_b32_e32 v156, 16, v191
	v_and_b32_e32 v155, 0xffff0000, v183
	v_lshlrev_b32_e32 v138, 16, v176
	v_and_b32_e32 v137, 0xffff0000, v168
	v_fmac_f32_e32 v147, v203, v143
	v_fma_f32 v148, v148, 0.5, -v152
	v_add_f32_e32 v149, v151, v149
	v_lshlrev_b32_e32 v158, 16, v187
	v_and_b32_e32 v157, 0xffff0000, v191
	v_lshlrev_b32_e32 v140, 16, v172
	v_and_b32_e32 v139, 0xffff0000, v176
	v_lshlrev_b32_e32 v142, 16, v169
	v_cvt_pk_bf16_f32 v217, v146, v147
	v_fmac_f32_e32 v152, v204, v148
	v_fma_f32 v149, v149, 0.5, -v153
	v_add_f32_e32 v154, v156, v154
	v_and_b32_e32 v159, 0xffff0000, v187
	ds_read_b128 v[180:183], v220 offset:35328
	ds_read_b128 v[184:187], v99 offset:35968
	ds_read_b128 v[188:191], v221 offset:36608
	v_add_f32_e32 v136, v138, v136
	v_and_b32_e32 v141, 0xffff0000, v172
	v_lshlrev_b32_e32 v144, 16, v177
	v_and_b32_e32 v143, 0xffff0000, v169
	v_fmac_f32_e32 v153, v205, v149
	v_fma_f32 v154, v154, 0.5, -v158
	v_add_f32_e32 v155, v157, v155
	v_fma_f32 v136, v136, 0.5, -v140
	v_add_f32_e32 v137, v139, v137
	v_lshlrev_b32_e32 v146, 16, v173
	v_and_b32_e32 v145, 0xffff0000, v177
	v_lshlrev_b32_e32 v148, 16, v170
	v_cvt_pk_bf16_f32 v218, v152, v153
	v_fmac_f32_e32 v158, v206, v154
	v_fma_f32 v155, v155, 0.5, -v159
	v_fmac_f32_e32 v140, v192, v136
	v_fma_f32 v137, v137, 0.5, -v141
	v_add_f32_e32 v142, v144, v142
	v_and_b32_e32 v147, 0xffff0000, v173
	v_lshlrev_b32_e32 v150, 16, v178
	v_and_b32_e32 v149, 0xffff0000, v170
	v_fmac_f32_e32 v159, v207, v155
	v_mul_f32_e32 v140, 0x4038aa3b, v140
	v_fmac_f32_e32 v141, v193, v137
	v_fma_f32 v142, v142, 0.5, -v146
	v_add_f32_e32 v143, v145, v143
	v_lshlrev_b32_e32 v152, 16, v174
	v_and_b32_e32 v151, 0xffff0000, v178
	v_lshlrev_b32_e32 v154, 16, v171
	v_cvt_pk_bf16_f32 v219, v158, v159
	ds_write_b128 v222, v[216:219] offset:24576
	v_exp_f32_e32 v140, v140
	v_mul_f32_e32 v141, 0x4038aa3b, v141
	v_fmac_f32_e32 v146, v194, v142
	v_fma_f32 v143, v143, 0.5, -v147
	v_add_f32_e32 v148, v150, v148
	v_and_b32_e32 v153, 0xffff0000, v174
	v_lshlrev_b32_e32 v156, 16, v179
	v_and_b32_e32 v155, 0xffff0000, v171
	v_add_f32_e32 v140, 1.0, v140
	v_exp_f32_e32 v141, v141
	v_mul_f32_e32 v146, 0x4038aa3b, v146
	v_fmac_f32_e32 v147, v195, v143
	v_fma_f32 v148, v148, 0.5, -v152
	v_add_f32_e32 v149, v151, v149
	v_lshlrev_b32_e32 v158, 16, v175
	v_and_b32_e32 v157, 0xffff0000, v179
	v_rcp_f32_e32 v140, v140
	v_add_f32_e32 v141, 1.0, v141
	v_exp_f32_e32 v146, v146
	v_mul_f32_e32 v147, 0x4038aa3b, v147
	v_fmac_f32_e32 v152, v196, v148
	v_fma_f32 v149, v149, 0.5, -v153
	v_add_f32_e32 v154, v156, v154
	v_and_b32_e32 v159, 0xffff0000, v175
	v_fma_f32 v140, -v140, 2.0, 1.0
	v_rcp_f32_e32 v141, v141
	v_add_f32_e32 v146, 1.0, v146
	v_exp_f32_e32 v147, v147
	v_mul_f32_e32 v152, 0x4038aa3b, v152
	v_fmac_f32_e32 v153, v197, v149
	v_fma_f32 v154, v154, 0.5, -v158
	v_add_f32_e32 v155, v157, v155
	v_fma_f32 v141, -v141, 2.0, 1.0
	v_rcp_f32_e32 v146, v146
	v_add_f32_e32 v147, 1.0, v147
	v_exp_f32_e32 v152, v152
	v_mul_f32_e32 v153, 0x4038aa3b, v153
	v_fmac_f32_e32 v158, v198, v154
	v_fma_f32 v155, v155, 0.5, -v159
	s_waitcnt lgkmcnt(1)
	v_lshlrev_b32_e32 v136, 16, v180
	v_cvt_pk_bf16_f32 v160, v140, v141
	v_fma_f32 v146, -v146, 2.0, 1.0
	v_rcp_f32_e32 v147, v147
	v_add_f32_e32 v152, 1.0, v152
	v_exp_f32_e32 v153, v153
	v_mul_f32_e32 v158, 0x4038aa3b, v158
	v_fmac_f32_e32 v159, v199, v155
	v_lshlrev_b32_e32 v138, 16, v188
	v_and_b32_e32 v137, 0xffff0000, v180
	v_fma_f32 v147, -v147, 2.0, 1.0
	v_rcp_f32_e32 v152, v152
	v_add_f32_e32 v153, 1.0, v153
	v_exp_f32_e32 v158, v158
	v_mul_f32_e32 v159, 0x4038aa3b, v159
	v_lshlrev_b32_e32 v140, 16, v184
	v_and_b32_e32 v139, 0xffff0000, v188
	v_lshlrev_b32_e32 v142, 16, v181
	v_cvt_pk_bf16_f32 v161, v146, v147
	v_fma_f32 v152, -v152, 2.0, 1.0
	v_rcp_f32_e32 v153, v153
	v_add_f32_e32 v158, 1.0, v158
	v_exp_f32_e32 v159, v159
	v_add_f32_e32 v136, v138, v136
	v_and_b32_e32 v141, 0xffff0000, v184
	v_lshlrev_b32_e32 v144, 16, v189
	v_and_b32_e32 v143, 0xffff0000, v181
	v_fma_f32 v153, -v153, 2.0, 1.0
	v_rcp_f32_e32 v158, v158
	v_add_f32_e32 v159, 1.0, v159
	v_fma_f32 v136, v136, 0.5, -v140
	v_add_f32_e32 v137, v139, v137
	v_lshlrev_b32_e32 v146, 16, v185
	v_and_b32_e32 v145, 0xffff0000, v189
	v_lshlrev_b32_e32 v148, 16, v182
	v_cvt_pk_bf16_f32 v162, v152, v153
	v_fma_f32 v158, -v158, 2.0, 1.0
	v_rcp_f32_e32 v159, v159
	v_fmac_f32_e32 v140, v200, v136
	v_fma_f32 v137, v137, 0.5, -v141
	v_add_f32_e32 v142, v144, v142
	v_and_b32_e32 v147, 0xffff0000, v185
	v_lshlrev_b32_e32 v150, 16, v190
	v_and_b32_e32 v149, 0xffff0000, v182
	v_fma_f32 v159, -v159, 2.0, 1.0
	v_fmac_f32_e32 v141, v201, v137
	v_fma_f32 v142, v142, 0.5, -v146
	v_add_f32_e32 v143, v145, v143
	v_lshlrev_b32_e32 v152, 16, v186
	v_and_b32_e32 v151, 0xffff0000, v190
	v_lshlrev_b32_e32 v154, 16, v183
	v_cvt_pk_bf16_f32 v163, v158, v159
	ds_write_b128 v223, v[160:163] offset:16384
	v_cvt_pk_bf16_f32 v216, v140, v141
	v_fmac_f32_e32 v146, v202, v142
	v_fma_f32 v143, v143, 0.5, -v147
	v_add_f32_e32 v148, v150, v148
	v_and_b32_e32 v153, 0xffff0000, v186
	v_lshlrev_b32_e32 v156, 16, v191
	v_and_b32_e32 v155, 0xffff0000, v183
	v_fmac_f32_e32 v147, v203, v143
	v_fma_f32 v148, v148, 0.5, -v152
	v_add_f32_e32 v149, v151, v149
	v_lshlrev_b32_e32 v158, 16, v187
	v_and_b32_e32 v157, 0xffff0000, v191
	v_cvt_pk_bf16_f32 v217, v146, v147
	v_fmac_f32_e32 v152, v204, v148
	v_fma_f32 v149, v149, 0.5, -v153
	v_add_f32_e32 v154, v156, v154
	v_and_b32_e32 v159, 0xffff0000, v187
	v_fmac_f32_e32 v153, v205, v149
	v_fma_f32 v154, v154, 0.5, -v158
	v_add_f32_e32 v155, v157, v155
	v_cvt_pk_bf16_f32 v218, v152, v153
	v_fmac_f32_e32 v158, v206, v154
	v_fma_f32 v155, v155, 0.5, -v159
	v_fmac_f32_e32 v159, v207, v155
	v_cvt_pk_bf16_f32 v219, v158, v159
	ds_write_b128 v223, v[216:219] offset:24576
	v_and_b32_e32 v160, 15, v1
	v_and_b32_e32 v161, -16, v1
	v_or_b32_e32 v162, s0, v160
	v_lshrrev_b32_e32 v163, 2, v1
	v_lshl_add_u32 v161, v162, 7, v161
	ds_read_b128 v[136:139], v161 offset:16384
	ds_read_b128 v[140:143], v161 offset:16448
	ds_read_b128 v[34:37], v224 offset:0
	ds_read_b128 v[38:41], v224 offset:1024
	ds_read_b128 v[42:45], v224 offset:2048
	ds_read_b128 v[46:49], v224 offset:3072
	ds_read_b128 v[50:53], v224 offset:4096
	ds_read_b128 v[54:57], v224 offset:5120
	ds_read_b128 v[58:61], v224 offset:6144
	ds_read_b128 v[62:65], v224 offset:7168
	v_lshlrev_b32_e32 v162, 2, v160
	v_and_b32_e32 v163, 0x1fffffc, v163
	v_add_u32_e32 v162, 0x22400, v162
	v_add_lshl_u32 v163, v163, s0, 7
	ds_read2_b32 v[152:153], v162 offset0:64 offset1:80
	ds_read2_b32 v[154:155], v162 offset0:96 offset1:112
	ds_read2_b32 v[156:157], v162 offset0:128 offset1:144
	ds_read2_b32 v[158:159], v162 offset0:160 offset1:176
	v_lshl_add_u32 v163, v160, 1, v163
	s_waitcnt lgkmcnt(10)
	v_mfma_f32_16x16x32_bf16 v[168:171], v[136:139], v[34:37], 0
	v_mfma_f32_16x16x32_bf16 v[168:171], v[140:143], v[38:41], v[168:171]
	s_waitcnt lgkmcnt(8)
	v_mfma_f32_16x16x32_bf16 v[172:175], v[136:139], v[42:45], 0
	v_mfma_f32_16x16x32_bf16 v[172:175], v[140:143], v[46:49], v[172:175]
	s_waitcnt lgkmcnt(0)
	ds_read_b128 v[144:147], v161 offset:24576
	ds_read_b128 v[148:151], v161 offset:24640
	ds_read_b128 v[66:69], v224 offset:8192
	ds_read_b128 v[70:73], v224 offset:9216
	ds_read_b128 v[74:77], v224 offset:10240
	ds_read_b128 v[78:81], v224 offset:11264
	ds_read_b128 v[82:85], v224 offset:12288
	ds_read_b128 v[86:89], v224 offset:13312
	ds_read_b128 v[90:93], v224 offset:14336
	ds_read_b128 v[94:97], v224 offset:15360
	s_nop 7
	v_add_f32_e32 v168, v168, v152
	v_mul_f32_e32 v168, 0xbfb8aa3b, v168
	v_add_f32_e32 v169, v169, v152
	v_exp_f32_e32 v168, v168
	v_mul_f32_e32 v169, 0xbfb8aa3b, v169
	v_add_f32_e32 v170, v170, v152
	v_add_f32_e32 v168, 1.0, v168
	v_exp_f32_e32 v169, v169
	v_mul_f32_e32 v170, 0xbfb8aa3b, v170
	v_add_f32_e32 v171, v171, v152
	v_rcp_f32_e32 v168, v168
	v_add_f32_e32 v169, 1.0, v169
	v_exp_f32_e32 v170, v170
	v_mul_f32_e32 v171, 0xbfb8aa3b, v171
	v_fma_mixlo_f16 v168, v168, s47, 0
	v_rcp_f32_e32 v169, v169
	v_add_f32_e32 v170, 1.0, v170
	v_exp_f32_e32 v171, v171
	ds_write_b16 v163, v168 offset:16384
	v_fma_mixlo_f16 v169, v169, s47, 0
	v_rcp_f32_e32 v170, v170
	v_add_f32_e32 v171, 1.0, v171
	ds_write_b16 v163, v169 offset:16512
	v_fma_mixlo_f16 v170, v170, s47, 0
	v_rcp_f32_e32 v171, v171
	ds_write_b16 v163, v170 offset:16640
	v_fma_mixlo_f16 v171, v171, s47, 0
	ds_write_b16 v163, v171 offset:16768
	v_mfma_f32_16x16x32_bf16 v[176:179], v[136:139], v[50:53], 0
	v_mfma_f32_16x16x32_bf16 v[176:179], v[140:143], v[54:57], v[176:179]
	v_add_f32_e32 v172, v172, v153
	v_mul_f32_e32 v172, 0xbfb8aa3b, v172
	v_add_f32_e32 v173, v173, v153
	v_exp_f32_e32 v172, v172
	v_mul_f32_e32 v173, 0xbfb8aa3b, v173
	v_add_f32_e32 v174, v174, v153
	v_add_f32_e32 v172, 1.0, v172
	v_exp_f32_e32 v173, v173
	v_mul_f32_e32 v174, 0xbfb8aa3b, v174
	v_add_f32_e32 v175, v175, v153
	v_rcp_f32_e32 v172, v172
	v_add_f32_e32 v173, 1.0, v173
	v_exp_f32_e32 v174, v174
	v_mul_f32_e32 v175, 0xbfb8aa3b, v175
	v_fma_mixlo_f16 v172, v172, s47, 0
	v_rcp_f32_e32 v173, v173
	v_add_f32_e32 v174, 1.0, v174
	v_exp_f32_e32 v175, v175
	ds_write_b16 v163, v172 offset:16416
	v_fma_mixlo_f16 v173, v173, s47, 0
	v_rcp_f32_e32 v174, v174
	v_add_f32_e32 v175, 1.0, v175
	ds_write_b16 v163, v173 offset:16544
	v_fma_mixlo_f16 v174, v174, s47, 0
	v_rcp_f32_e32 v175, v175
	ds_write_b16 v163, v174 offset:16672
	v_fma_mixlo_f16 v175, v175, s47, 0
	ds_write_b16 v163, v175 offset:16800
	v_mfma_f32_16x16x32_bf16 v[180:183], v[136:139], v[58:61], 0
	v_mfma_f32_16x16x32_bf16 v[180:183], v[140:143], v[62:65], v[180:183]
	v_add_f32_e32 v176, v176, v154
	v_mul_f32_e32 v176, 0xbfb8aa3b, v176
	v_add_f32_e32 v177, v177, v154
	v_exp_f32_e32 v176, v176
	v_mul_f32_e32 v177, 0xbfb8aa3b, v177
	v_add_f32_e32 v178, v178, v154
	v_add_f32_e32 v176, 1.0, v176
	v_exp_f32_e32 v177, v177
	v_mul_f32_e32 v178, 0xbfb8aa3b, v178
	v_add_f32_e32 v179, v179, v154
	v_rcp_f32_e32 v176, v176
	v_add_f32_e32 v177, 1.0, v177
	v_exp_f32_e32 v178, v178
	v_mul_f32_e32 v179, 0xbfb8aa3b, v179
	v_fma_mixlo_f16 v176, v176, s47, 0
	v_rcp_f32_e32 v177, v177
	v_add_f32_e32 v178, 1.0, v178
	v_exp_f32_e32 v179, v179
	ds_write_b16 v163, v176 offset:16448
	v_fma_mixlo_f16 v177, v177, s47, 0
	v_rcp_f32_e32 v178, v178
	v_add_f32_e32 v179, 1.0, v179
	ds_write_b16 v163, v177 offset:16576
	v_fma_mixlo_f16 v178, v178, s47, 0
	v_rcp_f32_e32 v179, v179
	ds_write_b16 v163, v178 offset:16704
	v_fma_mixlo_f16 v179, v179, s47, 0
	ds_write_b16 v163, v179 offset:16832
	s_waitcnt lgkmcnt(6)
	v_mfma_f32_16x16x32_bf16 v[184:187], v[144:147], v[66:69], 0
	v_mfma_f32_16x16x32_bf16 v[184:187], v[148:151], v[70:73], v[184:187]
	v_add_f32_e32 v180, v180, v155
	v_mul_f32_e32 v180, 0xbfb8aa3b, v180
	v_add_f32_e32 v181, v181, v155
	v_exp_f32_e32 v180, v180
	v_mul_f32_e32 v181, 0xbfb8aa3b, v181
	v_add_f32_e32 v182, v182, v155
	v_add_f32_e32 v180, 1.0, v180
	v_exp_f32_e32 v181, v181
	v_mul_f32_e32 v182, 0xbfb8aa3b, v182
	v_add_f32_e32 v183, v183, v155
	v_rcp_f32_e32 v180, v180
	v_add_f32_e32 v181, 1.0, v181
	v_exp_f32_e32 v182, v182
	v_mul_f32_e32 v183, 0xbfb8aa3b, v183
	v_fma_mixlo_f16 v180, v180, s47, 0
	v_rcp_f32_e32 v181, v181
	v_add_f32_e32 v182, 1.0, v182
	v_exp_f32_e32 v183, v183
	ds_write_b16 v163, v180 offset:16480
	v_fma_mixlo_f16 v181, v181, s47, 0
	v_rcp_f32_e32 v182, v182
	v_add_f32_e32 v183, 1.0, v183
	ds_write_b16 v163, v181 offset:16608
	v_fma_mixlo_f16 v182, v182, s47, 0
	v_rcp_f32_e32 v183, v183
	ds_write_b16 v163, v182 offset:16736
	v_fma_mixlo_f16 v183, v183, s47, 0
	ds_write_b16 v163, v183 offset:16864
	s_waitcnt lgkmcnt(4)
	v_mfma_f32_16x16x32_bf16 v[188:191], v[144:147], v[74:77], 0
	v_mfma_f32_16x16x32_bf16 v[188:191], v[148:151], v[78:81], v[188:191]
	v_add_f32_e32 v184, v184, v156
	v_mul_f32_e32 v184, 0xbfb8aa3b, v184
	v_add_f32_e32 v185, v185, v156
	v_exp_f32_e32 v184, v184
	v_mul_f32_e32 v185, 0xbfb8aa3b, v185
	v_add_f32_e32 v186, v186, v156
	v_add_f32_e32 v184, 1.0, v184
	v_exp_f32_e32 v185, v185
	v_mul_f32_e32 v186, 0xbfb8aa3b, v186
	v_add_f32_e32 v187, v187, v156
	v_rcp_f32_e32 v184, v184
	v_add_f32_e32 v185, 1.0, v185
	v_exp_f32_e32 v186, v186
	v_mul_f32_e32 v187, 0xbfb8aa3b, v187
	v_rcp_f32_e32 v185, v185
	v_add_f32_e32 v186, 1.0, v186
	v_exp_f32_e32 v187, v187
	v_cvt_pk_f16_f32 v184, v184, v185
	v_rcp_f32_e32 v186, v186
	v_add_f32_e32 v187, 1.0, v187
	ds_write_b16 v163, v184 offset:24576
	v_rcp_f32_e32 v187, v187
	ds_write_b16_d16_hi v163, v184 offset:24704
	v_cvt_pk_f16_f32 v186, v186, v187
	ds_write_b16 v163, v186 offset:24832
	ds_write_b16_d16_hi v163, v186 offset:24960
	s_waitcnt lgkmcnt(2)
	v_mfma_f32_16x16x32_bf16 v[192:195], v[144:147], v[82:85], 0
	v_mfma_f32_16x16x32_bf16 v[192:195], v[148:151], v[86:89], v[192:195]
	v_add_f32_e32 v188, v188, v157
	v_mul_f32_e32 v188, 0xbfb8aa3b, v188
	v_add_f32_e32 v189, v189, v157
	v_exp_f32_e32 v188, v188
	v_mul_f32_e32 v189, 0xbfb8aa3b, v189
	v_add_f32_e32 v190, v190, v157
	v_add_f32_e32 v188, 1.0, v188
	v_exp_f32_e32 v189, v189
	v_mul_f32_e32 v190, 0xbfb8aa3b, v190
	v_add_f32_e32 v191, v191, v157
	v_rcp_f32_e32 v188, v188
	v_add_f32_e32 v189, 1.0, v189
	v_exp_f32_e32 v190, v190
	v_mul_f32_e32 v191, 0xbfb8aa3b, v191
	v_rcp_f32_e32 v189, v189
	v_add_f32_e32 v190, 1.0, v190
	v_exp_f32_e32 v191, v191
	v_cvt_pk_f16_f32 v188, v188, v189
	v_rcp_f32_e32 v190, v190
	v_add_f32_e32 v191, 1.0, v191
	ds_write_b16 v163, v188 offset:24608
	v_rcp_f32_e32 v191, v191
	ds_write_b16_d16_hi v163, v188 offset:24736
	v_cvt_pk_f16_f32 v190, v190, v191
	ds_write_b16 v163, v190 offset:24864
	ds_write_b16_d16_hi v163, v190 offset:24992
	s_waitcnt lgkmcnt(0)
	v_mfma_f32_16x16x32_bf16 v[196:199], v[144:147], v[90:93], 0
	v_mfma_f32_16x16x32_bf16 v[196:199], v[148:151], v[94:97], v[196:199]
	v_add_f32_e32 v192, v192, v158
	v_mul_f32_e32 v192, 0xbfb8aa3b, v192
	v_add_f32_e32 v193, v193, v158
	v_exp_f32_e32 v192, v192
	v_mul_f32_e32 v193, 0xbfb8aa3b, v193
	v_add_f32_e32 v194, v194, v158
	v_add_f32_e32 v192, 1.0, v192
	v_exp_f32_e32 v193, v193
	v_mul_f32_e32 v194, 0xbfb8aa3b, v194
	v_add_f32_e32 v195, v195, v158
	v_rcp_f32_e32 v192, v192
	v_add_f32_e32 v193, 1.0, v193
	v_exp_f32_e32 v194, v194
	v_mul_f32_e32 v195, 0xbfb8aa3b, v195
	v_rcp_f32_e32 v193, v193
	v_add_f32_e32 v194, 1.0, v194
	v_exp_f32_e32 v195, v195
	v_cvt_pk_f16_f32 v192, v192, v193
	v_rcp_f32_e32 v194, v194
	v_add_f32_e32 v195, 1.0, v195
	ds_write_b16 v163, v192 offset:24640
	v_rcp_f32_e32 v195, v195
	ds_write_b16_d16_hi v163, v192 offset:24768
	v_cvt_pk_f16_f32 v194, v194, v195
	ds_write_b16 v163, v194 offset:24896
	ds_write_b16_d16_hi v163, v194 offset:25024
	v_add_f32_e32 v196, v196, v159
	v_mul_f32_e32 v196, 0xbfb8aa3b, v196
	v_add_f32_e32 v197, v197, v159
	v_exp_f32_e32 v196, v196
	v_mul_f32_e32 v197, 0xbfb8aa3b, v197
	v_add_f32_e32 v198, v198, v159
	v_add_f32_e32 v196, 1.0, v196
	v_exp_f32_e32 v197, v197
	v_mul_f32_e32 v198, 0xbfb8aa3b, v198
	v_add_f32_e32 v199, v199, v159
	v_rcp_f32_e32 v196, v196
	v_add_f32_e32 v197, 1.0, v197
	v_exp_f32_e32 v198, v198
	v_mul_f32_e32 v199, 0xbfb8aa3b, v199
	v_rcp_f32_e32 v197, v197
	v_add_f32_e32 v198, 1.0, v198
	v_exp_f32_e32 v199, v199
	v_cvt_pk_f16_f32 v196, v196, v197
	v_rcp_f32_e32 v198, v198
	v_add_f32_e32 v199, 1.0, v199
	ds_write_b16 v163, v196 offset:24672
	v_rcp_f32_e32 v199, v199
	ds_write_b16_d16_hi v163, v196 offset:24800
	v_cvt_pk_f16_f32 v198, v198, v199
	ds_write_b16 v163, v198 offset:24928
	ds_write_b16_d16_hi v163, v198 offset:25056

.LBB0_675:
	s_ashr_i32 s45, s44, 31
	s_lshl_b64 s[8:9], s[44:45], 19
	s_ashr_i32 s43, s42, 31
	v_lshl_add_u64 v[162:163], v[146:147], 0, s[8:9]
	s_lshl_b64 s[8:9], s[42:43], 19
	v_lshl_add_u64 v[164:165], v[140:141], 0, s[8:9]
	v_cndmask_b32_e64 v132, v2, v164, s[4:5]
	v_lshl_add_u64 v[136:137], v[2:3], 0, s[36:37]
	v_mov_b32_e32 v2, 0
	v_cndmask_b32_e64 v1, v5, v163, s[4:5]
	v_cndmask_b32_e64 v130, v4, v162, s[4:5]
	v_cndmask_b32_e64 v131, v3, v165, s[4:5]
	v_lshl_add_u64 v[134:135], v[4:5], 0, s[26:27]
	s_mov_b32 s3, -2
	v_mov_b32_e32 v3, v2
	v_mov_b64 v[4:5], 0
	v_mov_b64 v[6:7], 0
	v_mov_b64 v[8:9], 0
	v_mov_b64 v[18:19], 0
	v_mov_b64 v[20:21], 0
	v_mov_b64 v[22:23], 0
	v_mov_b64 v[24:25], 0
	v_mov_b64 v[34:35], 0
	v_mov_b64 v[36:37], 0
	v_mov_b64 v[38:39], 0
	v_mov_b64 v[40:41], 0
	v_mov_b64 v[50:51], 0
	v_mov_b64 v[52:53], 0
	v_mov_b64 v[54:55], 0
	v_mov_b64 v[56:57], 0
	v_mov_b64 v[10:11], 0
	v_mov_b64 v[12:13], 0
	v_mov_b64 v[14:15], 0
	v_mov_b64 v[16:17], 0
	v_mov_b64 v[26:27], 0
	v_mov_b64 v[28:29], 0
	v_mov_b64 v[30:31], 0
	v_mov_b64 v[32:33], 0
	v_mov_b64 v[42:43], 0
	v_mov_b64 v[44:45], 0
	v_mov_b64 v[46:47], 0
	v_mov_b64 v[48:49], 0
	v_mov_b64 v[58:59], 0
	v_mov_b64 v[60:61], 0
	v_mov_b64 v[62:63], 0
	v_mov_b64 v[64:65], 0
	v_mov_b64 v[66:67], 0
	v_mov_b64 v[68:69], 0
	v_mov_b64 v[70:71], 0
	v_mov_b64 v[72:73], 0
	v_mov_b64 v[82:83], 0
	v_mov_b64 v[84:85], 0
	v_mov_b64 v[86:87], 0
	v_mov_b64 v[88:89], 0
	v_mov_b64 v[98:99], 0
	v_mov_b64 v[100:101], 0
	v_mov_b64 v[102:103], 0
	v_mov_b64 v[104:105], 0
	v_mov_b64 v[114:115], 0
	v_mov_b64 v[116:117], 0
	v_mov_b64 v[118:119], 0
	v_mov_b64 v[120:121], 0
	v_mov_b64 v[74:75], 0
	v_mov_b64 v[76:77], 0
	v_mov_b64 v[78:79], 0
	v_mov_b64 v[80:81], 0
	v_mov_b64 v[90:91], 0
	v_mov_b64 v[92:93], 0
	v_mov_b64 v[94:95], 0
	v_mov_b64 v[96:97], 0
	v_mov_b64 v[106:107], 0
	v_mov_b64 v[108:109], 0
	v_mov_b64 v[110:111], 0
	v_mov_b64 v[112:113], 0
	v_mov_b64 v[122:123], 0
	v_mov_b64 v[124:125], 0
	v_mov_b64 v[126:127], 0
	v_mov_b64 v[128:129], 0

.LBB0_987:
	s_waitcnt lgkmcnt(0)
	v_add_f32_e32 v2, v2, v3
	v_mul_f32_e32 v3, 0x4f800000, v2
	v_cmp_gt_f32_e32 vcc, s36, v2
	s_lshl_b32 s26, s42, 7
	s_add_i32 s42, s29, 0x2000
	v_cndmask_b32_e32 v2, v2, v3, vcc
	v_sqrt_f32_e32 v3, v2
	v_mov_b32_e32 v139, 0
	v_lshl_add_u32 v141, s41, 13, v154
	v_mov_b32_e32 v7, v139
	v_add_u32_e32 v5, -1, v3
	v_fma_f32 v6, -v5, v3, v2
	v_cmp_ge_f32_e64 s[4:5], 0, v6
	v_add_u32_e32 v6, 1, v3
	v_mov_b32_e32 v8, v139
	v_cndmask_b32_e64 v5, v3, v5, s[4:5]
	v_fma_f32 v3, -v6, v3, v2
	v_cmp_lt_f32_e64 s[4:5], 0, v3
	v_mov_b32_e32 v9, v139
	v_mov_b32_e32 v10, v139
	v_cndmask_b32_e64 v3, v5, v6, s[4:5]
	v_mul_f32_e32 v5, 0x37800000, v3
	v_cndmask_b32_e32 v3, v3, v5, vcc
	v_cmp_class_f32_e32 vcc, v2, v156
	s_add_i32 s4, s44, 1
	s_and_b32 s5, s45, 0x3ffffff0
	v_cndmask_b32_e32 v2, v3, v2, vcc
	v_mul_f32_e64 v66, v2, -v4
	v_lshl_add_u64 v[2:3], s[22:23], 0, v[134:135]
	s_add_u32 s22, s6, s5
	s_addc_u32 s23, 0, 0
	v_lshl_add_u64 v[144:145], v[2:3], 0, s[22:23]
	s_add_u32 s22, s6, s28
	s_addc_u32 s23, 0, 0
	s_lshl_b32 s5, s43, 9
	s_and_b32 s5, s5, 0x18000
	v_lshl_or_b32 v4, v155, 1, s5
	v_mov_b32_e32 v5, v131
	v_lshl_add_u64 v[2:3], s[24:25], 0, v[136:137]
	v_lshl_add_u64 v[4:5], s[22:23], 0, v[4:5]
	v_mov_b32_e32 v67, v66
	v_mov_b32_e32 v68, v66
	v_mov_b32_e32 v69, v66
	v_mov_b32_e32 v70, v66
	v_mov_b32_e32 v71, v66
	v_mov_b32_e32 v72, v66
	v_mov_b32_e32 v73, v66
	v_mov_b32_e32 v74, v66
	v_mov_b32_e32 v75, v66
	v_mov_b32_e32 v76, v66
	v_mov_b32_e32 v77, v66
	v_mov_b32_e32 v78, v66
	v_mov_b32_e32 v79, v66
	v_mov_b32_e32 v80, v66
	v_mov_b32_e32 v81, v66
	v_lshl_add_u64 v[146:147], v[2:3], 0, v[4:5]
	s_mov_b32 s6, 0
	v_mov_b64 v[2:3], 0
	v_mov_b64 v[4:5], 0
	v_mov_b32_e32 v6, v139
	v_mov_b32_e32 v11, v139
	v_mov_b64 v[12:13], 0
	v_mov_b64 v[14:15], 0
	v_mov_b64 v[16:17], 0
	v_mov_b64 v[18:19], 0
	v_mov_b64 v[20:21], 0
	v_mov_b64 v[22:23], 0
	v_mov_b64 v[24:25], 0
	v_mov_b64 v[26:27], 0
	v_mov_b64 v[28:29], 0
	v_mov_b64 v[30:31], 0
	v_mov_b64 v[32:33], 0
	v_mov_b64 v[34:35], 0
	v_mov_b64 v[36:37], 0
	v_mov_b64 v[38:39], 0
	v_mov_b64 v[40:41], 0
	v_mov_b64 v[42:43], 0
	v_mov_b64 v[44:45], 0
	v_mov_b64 v[46:47], 0
	v_mov_b64 v[48:49], 0
	v_mov_b64 v[50:51], 0
	v_mov_b64 v[52:53], 0
	v_mov_b64 v[54:55], 0
	v_mov_b64 v[56:57], 0
	v_mov_b64 v[58:59], 0
	v_mov_b64 v[60:61], 0
	v_mov_b64 v[62:63], 0
	v_mov_b64 v[64:65], 0
	s_movk_i32 s23, 0x4000
	s_mov_b32 s28, m0
	s_add_i32 s24, s23, s29
	s_mov_b32 m0, s24
	s_add_i32 s25, s23, s42
	global_load_lds_dwordx4 v[144:145], off
	s_addk_i32 s25, 0xff80
	s_mov_b32 m0, s25
	s_add_i32 s24, s24, 0xc000
	global_load_lds_dwordx4 v[144:145], off offset:128
	s_mov_b32 m0, s24
	s_add_i32 s25, s25, 0xc000
	global_load_lds_dwordx4 v[146:147], off
	s_mov_b32 m0, s25
	v_lshl_add_u64 v[144:145], v[144:145], 0, s[18:19]
	global_load_lds_dwordx4 v[146:147], off offset:128
	s_mov_b32 m0, s28
	v_lshl_add_u64 v[146:147], v[146:147], 0, s[18:19]
	s_waitcnt vmcnt(4) lgkmcnt(0)
	s_barrier
	v_mov_b32_e32 v159, v141
	ds_read_b128 v[210:213], v159
	ds_read_b128 v[214:217], v159 offset:512
	ds_read_b128 v[218:221], v159 offset:2048
	ds_read_b128 v[222:225], v159 offset:2560
	ds_read_b128 v[226:229], v159 offset:4096
	ds_read_b128 v[230:233], v159 offset:4608
	ds_read_b128 v[234:237], v159 offset:6144
	ds_read_b128 v[238:241], v159 offset:6656
	s_waitcnt lgkmcnt(7)
	v_mfma_f32_32x32x16_bf16 v[98:113], v[210:213], v[126:129], v[66:81]
	s_waitcnt lgkmcnt(5)
	v_mfma_f32_32x32x16_bf16 v[98:113], v[218:221], v[122:125], v[98:113]
	s_waitcnt lgkmcnt(3)
	v_mfma_f32_32x32x16_bf16 v[98:113], v[226:229], v[118:121], v[98:113]
	s_waitcnt lgkmcnt(1)
	v_mfma_f32_32x32x16_bf16 v[98:113], v[234:237], v[114:117], v[98:113]
	v_mfma_f32_32x32x16_bf16 v[82:97], v[214:217], v[126:129], v[66:81]
	v_mfma_f32_32x32x16_bf16 v[82:97], v[222:225], v[122:125], v[82:97]
	v_mfma_f32_32x32x16_bf16 v[82:97], v[230:233], v[118:121], v[82:97]
	s_waitcnt lgkmcnt(0)
	v_mfma_f32_32x32x16_bf16 v[82:97], v[238:241], v[114:117], v[82:97]
	s_nop 6
	v_exp_f32_e32 v98, v98
	v_exp_f32_e32 v99, v99
	v_exp_f32_e32 v100, v100
	v_exp_f32_e32 v101, v101
	v_exp_f32_e32 v102, v102
	v_exp_f32_e32 v103, v103
	v_exp_f32_e32 v104, v104
	v_exp_f32_e32 v105, v105
	v_exp_f32_e32 v106, v106
	v_exp_f32_e32 v107, v107
	v_exp_f32_e32 v108, v108
	v_exp_f32_e32 v109, v109
	v_exp_f32_e32 v110, v110
	v_exp_f32_e32 v111, v111
	v_exp_f32_e32 v112, v112
	v_exp_f32_e32 v113, v113
	v_exp_f32_e32 v82, v82
	v_exp_f32_e32 v83, v83
	v_exp_f32_e32 v84, v84
	v_exp_f32_e32 v85, v85
	v_exp_f32_e32 v86, v86
	v_exp_f32_e32 v87, v87
	v_exp_f32_e32 v88, v88
	v_exp_f32_e32 v89, v89
	v_exp_f32_e32 v90, v90
	v_exp_f32_e32 v91, v91
	v_exp_f32_e32 v92, v92
	v_exp_f32_e32 v93, v93
	v_exp_f32_e32 v94, v94
	v_exp_f32_e32 v95, v95
	v_exp_f32_e32 v96, v96
	v_exp_f32_e32 v97, v97
	v_cvt_pk_bf16_f32 v194, v98, v99
	v_cvt_pk_bf16_f32 v195, v100, v101
	v_cvt_pk_bf16_f32 v196, v102, v103
	v_cvt_pk_bf16_f32 v197, v104, v105
	v_cvt_pk_bf16_f32 v198, v106, v107
	v_cvt_pk_bf16_f32 v199, v108, v109
	v_cvt_pk_bf16_f32 v200, v110, v111
	v_cvt_pk_bf16_f32 v201, v112, v113
	v_cvt_pk_bf16_f32 v202, v82, v83
	v_cvt_pk_bf16_f32 v203, v84, v85
	v_cvt_pk_bf16_f32 v204, v86, v87
	v_cvt_pk_bf16_f32 v205, v88, v89
	v_cvt_pk_bf16_f32 v206, v90, v91
	v_cvt_pk_bf16_f32 v207, v92, v93
	v_cvt_pk_bf16_f32 v208, v94, v95
	v_cvt_pk_bf16_f32 v209, v96, v97
	s_mov_b32 s6, 0

.LBB0_1064:
	s_ashr_i32 s47, s46, 31
	s_lshl_b64 s[12:13], s[46:47], 20
	s_ashr_i32 s49, s48, 31
	s_ashr_i32 s45, s44, 31
	v_lshl_add_u64 v[6:7], v[168:169], 0, s[12:13]
	s_lshl_b64 s[12:13], s[48:49], 7
	s_lshl_b64 s[52:53], s[44:45], 20
	v_lshl_add_u64 v[188:189], v[6:7], 0, s[12:13]
	v_lshl_add_u64 v[6:7], v[170:171], 0, s[52:53]
	v_lshl_add_u64 v[190:191], v[6:7], 0, s[12:13]
	s_waitcnt vmcnt(0)
	v_mov_b32_e32 v66, 0
	v_cndmask_b32_e64 v1, v5, v189, s[50:51]
	v_cndmask_b32_e64 v130, v4, v188, s[50:51]
	v_cndmask_b32_e64 v131, v3, v191, s[50:51]
	v_cndmask_b32_e64 v132, v2, v190, s[50:51]
	s_add_i32 s12, s9, -2
	v_lshl_add_u64 v[134:135], v[4:5], 0, s[24:25]
	v_lshl_add_u64 v[136:137], v[2:3], 0, s[38:39]
	s_mov_b32 s13, 0
	v_mov_b32_e32 v67, v66
	v_mov_b64 v[68:69], 0
	v_mov_b64 v[70:71], 0
	v_mov_b64 v[72:73], 0
	v_mov_b64 v[74:75], 0
	v_mov_b64 v[76:77], 0
	v_mov_b64 v[78:79], 0
	v_mov_b64 v[80:81], 0
	v_mov_b64 v[82:83], 0
	v_mov_b64 v[84:85], 0
	v_mov_b64 v[86:87], 0
	v_mov_b64 v[88:89], 0
	v_mov_b64 v[90:91], 0
	v_mov_b64 v[92:93], 0
	v_mov_b64 v[94:95], 0
	v_mov_b64 v[96:97], 0
	v_mov_b64 v[98:99], 0
	v_mov_b64 v[100:101], 0
	v_mov_b64 v[102:103], 0
	v_mov_b64 v[104:105], 0
	v_mov_b64 v[106:107], 0
	v_mov_b64 v[108:109], 0
	v_mov_b64 v[110:111], 0
	v_mov_b64 v[112:113], 0
	v_mov_b64 v[114:115], 0
	v_mov_b64 v[116:117], 0
	v_mov_b64 v[118:119], 0
	v_mov_b64 v[120:121], 0
	v_mov_b64 v[122:123], 0
	v_mov_b64 v[124:125], 0
	v_mov_b64 v[126:127], 0
	v_mov_b64 v[128:129], 0
	v_mov_b64 v[2:3], 0
	v_mov_b64 v[4:5], 0
	v_mov_b64 v[6:7], 0
	v_mov_b64 v[8:9], 0
	v_mov_b64 v[10:11], 0
	v_mov_b64 v[12:13], 0
	v_mov_b64 v[14:15], 0
	v_mov_b64 v[16:17], 0
	v_mov_b64 v[18:19], 0
	v_mov_b64 v[20:21], 0
	v_mov_b64 v[22:23], 0
	v_mov_b64 v[24:25], 0
	v_mov_b64 v[26:27], 0
	v_mov_b64 v[28:29], 0
	v_mov_b64 v[30:31], 0
	v_mov_b64 v[32:33], 0
	v_mov_b64 v[34:35], 0
	v_mov_b64 v[36:37], 0
	v_mov_b64 v[38:39], 0
	v_mov_b64 v[40:41], 0
	v_mov_b64 v[42:43], 0
	v_mov_b64 v[44:45], 0
	v_mov_b64 v[46:47], 0
	v_mov_b64 v[48:49], 0
	v_mov_b64 v[50:51], 0
	v_mov_b64 v[52:53], 0
	v_mov_b64 v[54:55], 0
	v_mov_b64 v[56:57], 0
	v_mov_b64 v[58:59], 0
	v_mov_b64 v[60:61], 0
	v_mov_b64 v[62:63], 0
	v_mov_b64 v[64:65], 0

.LBB0_1095:
	s_cmpk_gt_i32 s58, 0x7ff
	s_waitcnt vmcnt(0)
	s_barrier
	s_cbranch_scc1 .LBB0_1102
	s_ashr_i32 s0, s58, 31
	s_lshr_b32 s0, s0, 28
	s_add_i32 s0, s58, s0
	s_load_dwordx2 s[4:5], s[60:61], 0xd8
	s_and_b32 s1, s0, 0x3fffff0
	s_ashr_i32 s2, s0, 4
	s_sub_i32 s1, s58, s1
	v_lshl_or_b32 v2, s2, 6, v202
	v_bfe_u32 v1, v0, 4, 1
	v_lshrrev_b32_e32 v26, 6, v0
	v_and_or_b32 v3, s2, 2, v1
	s_andn2_b32 s0, s0, 63
	v_lshrrev_b32_e32 v2, 1, v2
	v_lshl_or_b32 v4, s1, 6, v26
	v_lshl_add_u32 v3, v3, 11, s0
	v_and_b32_e32 v2, 48, v2
	v_ashrrev_i32_e32 v5, 31, v4
	v_or3_b32 v2, v3, v2, v201
	v_lshlrev_b64 v[4:5], 15, v[4:5]
	s_waitcnt lgkmcnt(0)
	v_lshl_add_u64 v[4:5], s[4:5], 0, v[4:5]
	v_ashrrev_i32_e32 v3, 31, v2
	v_lshl_add_u64 v[2:3], v[2:3], 2, v[4:5]
	s_mov_b32 s0, 0x40000
	v_add_co_u32_e32 v4, vcc, s0, v2
	s_mov_b32 s1, 0x80000
	s_nop 0
	v_addc_co_u32_e32 v5, vcc, 0, v3, vcc
	v_add_co_u32_e32 v6, vcc, s1, v2
	s_mov_b32 s2, 0xc0000
	s_nop 0
	v_addc_co_u32_e32 v7, vcc, 0, v3, vcc
	v_add_co_u32_e32 v8, vcc, s2, v2
	s_mov_b32 s3, 0x100000
	s_nop 0
	v_addc_co_u32_e32 v9, vcc, 0, v3, vcc
	v_add_co_u32_e32 v10, vcc, s3, v2
	s_mov_b32 s3, 0x140000
	s_nop 0
	v_addc_co_u32_e32 v11, vcc, 0, v3, vcc
	v_add_co_u32_e32 v12, vcc, s3, v2
	s_mov_b32 s3, 0x180000
	s_nop 0
	v_addc_co_u32_e32 v13, vcc, 0, v3, vcc
	v_add_co_u32_e32 v14, vcc, s3, v2
	s_mov_b32 s3, 0x1c0000
	s_nop 0
	v_addc_co_u32_e32 v15, vcc, 0, v3, vcc
	v_add_co_u32_e32 v16, vcc, s3, v2
	s_mov_b64 s[6:7], 0x800000
	s_nop 0
	v_addc_co_u32_e32 v17, vcc, 0, v3, vcc
	global_load_dword v18, v[2:3], off
	global_load_dword v19, v[4:5], off
	global_load_dword v20, v[6:7], off
	global_load_dword v21, v[8:9], off
	global_load_dword v22, v[10:11], off
	global_load_dword v23, v[12:13], off
	global_load_dword v24, v[14:15], off
	global_load_dword v25, v[16:17], off
	v_lshlrev_b32_e32 v4, 3, v0
	v_and_b32_e32 v4, 56, v4
	v_and_b32_e32 v6, 63, v0
	v_mul_u32_u24_e32 v5, 0x104, v4
	v_lshlrev_b32_e32 v7, 2, v200
	v_lshl_add_u32 v9, v6, 2, 0
	v_add3_u32 v7, 0, v5, v7
	v_mov_b32_e32 v5, 0
	v_mul_u32_u24_e32 v10, 0x104, v26
	s_lshl_b32 s8, s73, 6
	v_lshl_add_u64 v[2:3], v[166:167], 0, s[6:7]
	s_lshl_b32 s3, s58, 6
	v_or_b32_e32 v8, s8, v26
	v_add_u32_e32 v9, v9, v10
	s_movk_i32 s9, 0x7fff
	s_mov_b32 s10, 0xffff0000
	v_lshlrev_b32_e32 v4, 1, v4
	s_mov_b32 s12, s58
	v_mov_b64 v[10:11], 0
	v_mov_b64 v[12:13], 0
	v_mov_b64 v[14:15], 0
	v_mov_b64 v[16:17], 0
	s_branch .LBB0_1098

.LBB0_1103:
	s_sub_i32 s8, 0x140, s73
	s_cmpk_gt_i32 s73, 0x140
	s_cselect_b64 s[0:1], -1, 0
	s_cmp_le_i32 s73, s8
	s_cselect_b64 s[2:3], -1, 0
	s_or_b64 s[4:5], s[0:1], s[2:3]
	s_cmp_lt_i32 s75, s8
	s_cselect_b64 s[0:1], -1, 0
	s_or_b64 s[0:1], s[4:5], s[0:1]
	s_mov_b64 s[6:7], -1
	s_and_b64 vcc, exec, s[0:1]
	s_cbranch_vccnz .LBB0_1110
	s_sub_i32 s3, s75, s8
	s_cmpk_gt_i32 s3, 0x7ff
	s_waitcnt vmcnt(0)
	s_barrier
	s_cbranch_scc1 .LBB0_1109
	s_ashr_i32 s0, s3, 31
	s_lshr_b32 s0, s0, 28
	s_add_i32 s0, s3, s0
	s_load_dwordx2 s[6:7], s[60:61], 0xd8
	s_ashr_i32 s1, s0, 4
	s_and_b32 s2, s0, 0x3fffff0
	s_sub_i32 s2, s3, s2
	v_lshl_or_b32 v2, s1, 6, v202
	v_bfe_u32 v1, v0, 4, 1
	v_lshrrev_b32_e32 v26, 6, v0
	v_and_or_b32 v3, s1, 2, v1
	s_andn2_b32 s0, s0, 63
	v_lshrrev_b32_e32 v2, 1, v2
	v_lshl_or_b32 v4, s2, 6, v26
	v_lshl_add_u32 v3, v3, 11, s0
	v_and_b32_e32 v2, 48, v2
	v_ashrrev_i32_e32 v5, 31, v4
	v_or3_b32 v2, v3, v2, v201
	v_lshlrev_b64 v[4:5], 15, v[4:5]
	s_waitcnt lgkmcnt(0)
	v_lshl_add_u64 v[4:5], s[6:7], 0, v[4:5]
	v_ashrrev_i32_e32 v3, 31, v2
	v_lshl_add_u64 v[2:3], v[2:3], 2, v[4:5]
	s_mov_b32 s0, 0x40000
	v_add_co_u32_e32 v4, vcc, s0, v2
	s_mov_b32 s1, 0x80000
	s_nop 0
	v_addc_co_u32_e32 v5, vcc, 0, v3, vcc
	v_add_co_u32_e32 v6, vcc, s1, v2
	s_mov_b32 s2, 0xc0000
	s_nop 0
	v_addc_co_u32_e32 v7, vcc, 0, v3, vcc
	v_add_co_u32_e32 v8, vcc, s2, v2
	s_mov_b32 s9, 0x100000
	s_nop 0
	v_addc_co_u32_e32 v9, vcc, 0, v3, vcc
	v_add_co_u32_e32 v10, vcc, s9, v2
	s_mov_b32 s9, 0x140000
	s_nop 0
	v_addc_co_u32_e32 v11, vcc, 0, v3, vcc
	v_add_co_u32_e32 v12, vcc, s9, v2
	s_mov_b32 s9, 0x180000
	s_nop 0
	v_addc_co_u32_e32 v13, vcc, 0, v3, vcc
	v_add_co_u32_e32 v14, vcc, s9, v2
	s_mov_b32 s9, 0x1c0000
	s_nop 0
	v_addc_co_u32_e32 v15, vcc, 0, v3, vcc
	v_add_co_u32_e32 v16, vcc, s9, v2
	s_mov_b64 s[10:11], 0x800000
	s_nop 0
	v_addc_co_u32_e32 v17, vcc, 0, v3, vcc
	global_load_dword v18, v[2:3], off
	global_load_dword v19, v[4:5], off
	global_load_dword v20, v[6:7], off
	global_load_dword v21, v[8:9], off
	global_load_dword v22, v[10:11], off
	global_load_dword v23, v[12:13], off
	global_load_dword v24, v[14:15], off
	global_load_dword v25, v[16:17], off
	v_lshlrev_b32_e32 v4, 3, v0
	v_and_b32_e32 v4, 56, v4
	v_lshl_add_u64 v[2:3], v[166:167], 0, s[10:11]
	s_sub_i32 s10, s73, s8
	v_and_b32_e32 v6, 63, v0
	v_mul_u32_u24_e32 v5, 0x104, v4
	v_lshlrev_b32_e32 v7, 2, v200
	v_lshl_add_u32 v9, v6, 2, 0
	v_add3_u32 v7, 0, v5, v7
	v_mov_b32_e32 v5, 0
	v_mul_u32_u24_e32 v10, 0x104, v26
	s_lshl_b32 s12, s10, 6
	s_lshl_b32 s11, s3, 6
	v_or_b32_e32 v8, s12, v26
	v_add_u32_e32 v9, v9, v10
	s_movk_i32 s13, 0x7fff
	s_mov_b32 s16, 0xffff0000
	v_lshlrev_b32_e32 v4, 1, v4
	v_mov_b64 v[10:11], 0
	v_mov_b64 v[12:13], 0
	v_mov_b64 v[14:15], 0
	v_mov_b64 v[16:17], 0
	s_branch .LBB0_1107

.LBB0_1110:
	s_andn2_b64 vcc, exec, s[6:7]
	s_cbranch_vccnz .LBB0_1117
	s_andn2_b64 vcc, exec, s[4:5]
	s_cbranch_vccnz .LBB0_1117
	s_cmpk_gt_i32 s58, 0x7ff
	s_waitcnt vmcnt(0)
	s_barrier
	s_cbranch_scc1 .LBB0_1117
	s_ashr_i32 s0, s58, 31
	s_lshr_b32 s0, s0, 28
	s_add_i32 s0, s58, s0
	s_load_dwordx2 s[4:5], s[60:61], 0xd8
	s_ashr_i32 s1, s0, 4
	s_and_b32 s2, s0, 0x3fffff0
	s_sub_i32 s2, s58, s2
	v_lshl_or_b32 v2, s1, 6, v202
	v_bfe_u32 v1, v0, 4, 1
	v_lshrrev_b32_e32 v26, 6, v0
	v_and_or_b32 v3, s1, 2, v1
	s_andn2_b32 s0, s0, 63
	v_lshrrev_b32_e32 v2, 1, v2
	v_lshl_or_b32 v4, s2, 6, v26
	v_lshl_add_u32 v3, v3, 11, s0
	v_and_b32_e32 v2, 48, v2
	v_ashrrev_i32_e32 v5, 31, v4
	v_or3_b32 v2, v3, v2, v201
	v_lshlrev_b64 v[4:5], 15, v[4:5]
	s_waitcnt lgkmcnt(0)
	v_lshl_add_u64 v[4:5], s[4:5], 0, v[4:5]
	v_ashrrev_i32_e32 v3, 31, v2
	v_lshl_add_u64 v[2:3], v[2:3], 2, v[4:5]
	s_mov_b32 s0, 0x40000
	v_add_co_u32_e32 v4, vcc, s0, v2
	s_mov_b32 s1, 0x80000
	s_nop 0
	v_addc_co_u32_e32 v5, vcc, 0, v3, vcc
	v_add_co_u32_e32 v6, vcc, s1, v2
	s_mov_b32 s2, 0xc0000
	s_nop 0
	v_addc_co_u32_e32 v7, vcc, 0, v3, vcc
	v_add_co_u32_e32 v8, vcc, s2, v2
	s_mov_b32 s3, 0x100000
	s_nop 0
	v_addc_co_u32_e32 v9, vcc, 0, v3, vcc
	v_add_co_u32_e32 v10, vcc, s3, v2
	s_mov_b32 s3, 0x140000
	s_nop 0
	v_addc_co_u32_e32 v11, vcc, 0, v3, vcc
	v_add_co_u32_e32 v12, vcc, s3, v2
	s_mov_b32 s3, 0x180000
	s_nop 0
	v_addc_co_u32_e32 v13, vcc, 0, v3, vcc
	v_add_co_u32_e32 v14, vcc, s3, v2
	s_mov_b32 s3, 0x1c0000
	s_nop 0
	v_addc_co_u32_e32 v15, vcc, 0, v3, vcc
	v_add_co_u32_e32 v16, vcc, s3, v2
	s_mov_b64 s[6:7], 0x800000
	s_nop 0
	v_addc_co_u32_e32 v17, vcc, 0, v3, vcc
	global_load_dword v18, v[2:3], off
	global_load_dword v19, v[4:5], off
	global_load_dword v20, v[6:7], off
	global_load_dword v21, v[8:9], off
	global_load_dword v22, v[10:11], off
	global_load_dword v23, v[12:13], off
	global_load_dword v24, v[14:15], off
	global_load_dword v25, v[16:17], off
	v_lshlrev_b32_e32 v4, 3, v0
	v_and_b32_e32 v4, 56, v4
	v_and_b32_e32 v6, 63, v0
	v_mul_u32_u24_e32 v5, 0x104, v4
	v_lshlrev_b32_e32 v7, 2, v200
	v_lshl_add_u32 v9, v6, 2, 0
	v_add3_u32 v7, 0, v5, v7
	v_mov_b32_e32 v5, 0
	v_mul_u32_u24_e32 v10, 0x104, v26
	s_lshl_b32 s8, s73, 6
	v_lshl_add_u64 v[2:3], v[166:167], 0, s[6:7]
	s_lshl_b32 s3, s58, 6
	v_or_b32_e32 v8, s8, v26
	v_add_u32_e32 v9, v9, v10
	s_movk_i32 s9, 0x7fff
	s_mov_b32 s10, 0xffff0000
	v_lshlrev_b32_e32 v4, 1, v4
	s_mov_b32 s12, s58
	v_mov_b64 v[10:11], 0
	v_mov_b64 v[12:13], 0
	v_mov_b64 v[14:15], 0
	v_mov_b64 v[16:17], 0
	s_add_i32 s26, s12, s73
	s_cmpk_gt_i32 s26, 0x7ff
	s_cbranch_scc1 .Lcv2_A
	s_ashr_i32 s13, s26, 31
	s_lshr_b32 s13, s13, 28
	s_add_i32 s13, s26, s13
	s_ashr_i32 s16, s13, 4
	v_lshl_or_b32 v60, s16, 6, v6
	v_and_or_b32 v61, s16, 2, v1
	s_andn2_b32 s13, s13, 63
	v_lshrrev_b32_e32 v60, 1, v60
	v_lshl_add_u32 v61, v61, 11, s13
	v_and_b32_e32 v60, 48, v60
	v_or3_b32 v60, v61, v60, v201
	v_add_u32_e32 v61, s3, v8
	s_lshl_b32 s13, s16, 10
	v_subrev_u32_e32 v62, s13, v61
	v_ashrrev_i32_e32 v63, 31, v62
	v_lshlrev_b64 v[62:63], 15, v[62:63]
	v_lshl_add_u64 v[62:63], s[4:5], 0, v[62:63]
	v_ashrrev_i32_e32 v61, 31, v60
	v_lshl_add_u64 v[64:65], v[60:61], 2, v[62:63]
	v_add_co_u32_e32 v66, vcc, s0, v64
	s_nop 1
	v_addc_co_u32_e32 v67, vcc, 0, v65, vcc
	v_add_co_u32_e32 v68, vcc, s1, v64
	s_nop 1
	v_addc_co_u32_e32 v69, vcc, 0, v65, vcc
	v_add_co_u32_e32 v70, vcc, s2, v64
	s_nop 1
	v_addc_co_u32_e32 v71, vcc, 0, v65, vcc
	v_add_co_u32_e32 v72, vcc, 0x100000, v64
	s_nop 1
	v_addc_co_u32_e32 v73, vcc, 0, v65, vcc
	v_add_co_u32_e32 v74, vcc, 0x140000, v64
	s_nop 1
	v_addc_co_u32_e32 v75, vcc, 0, v65, vcc
	v_add_co_u32_e32 v76, vcc, 0x180000, v64
	s_nop 1
	v_addc_co_u32_e32 v77, vcc, 0, v65, vcc
	v_add_co_u32_e32 v78, vcc, 0x1c0000, v64
	s_nop 1
	v_addc_co_u32_e32 v79, vcc, 0, v65, vcc
	global_load_dword v10, v[64:65], off
	global_load_dword v11, v[66:67], off
	global_load_dword v12, v[68:69], off
	global_load_dword v13, v[70:71], off
	global_load_dword v14, v[72:73], off
	global_load_dword v15, v[74:75], off
	global_load_dword v16, v[76:77], off
	global_load_dword v17, v[78:79], off

.LBB0_1251:
	s_ashr_i32 s47, s46, 31
	s_lshl_b64 s[8:9], s[46:47], 19
	s_ashr_i32 s45, s44, 31
	v_lshl_add_u64 v[170:171], v[146:147], 0, s[8:9]
	s_lshl_b64 s[8:9], s[44:45], 19
	v_lshl_add_u64 v[172:173], v[148:149], 0, s[8:9]
	s_waitcnt vmcnt(0)
	v_cndmask_b32_e64 v84, v2, v172, s[4:5]
	v_lshl_add_u64 v[88:89], v[2:3], 0, s[40:41]
	v_mov_b32_e32 v2, 0
	v_cndmask_b32_e64 v1, v5, v171, s[4:5]
	v_cndmask_b32_e64 v82, v4, v170, s[4:5]
	v_cndmask_b32_e64 v83, v3, v173, s[4:5]
	v_lshl_add_u64 v[86:87], v[4:5], 0, s[28:29]
	s_mov_b32 s7, -2
	v_mov_b32_e32 v3, v2
	v_mov_b64 v[4:5], 0
	v_mov_b64 v[114:115], 0
	v_mov_b64 v[116:117], 0
	v_mov_b64 v[10:11], 0
	v_mov_b64 v[12:13], 0
	v_mov_b64 v[54:55], 0
	v_mov_b64 v[56:57], 0
	v_mov_b64 v[18:19], 0
	v_mov_b64 v[20:21], 0
	v_mov_b64 v[58:59], 0
	v_mov_b64 v[60:61], 0
	v_mov_b64 v[26:27], 0
	v_mov_b64 v[28:29], 0
	v_mov_b64 v[122:123], 0
	v_mov_b64 v[124:125], 0
	v_mov_b64 v[118:119], 0
	v_mov_b64 v[120:121], 0
	v_mov_b64 v[6:7], 0
	v_mov_b64 v[8:9], 0
	v_mov_b64 v[66:67], 0
	v_mov_b64 v[68:69], 0
	v_mov_b64 v[14:15], 0
	v_mov_b64 v[16:17], 0
	v_mov_b64 v[70:71], 0
	v_mov_b64 v[72:73], 0
	v_mov_b64 v[22:23], 0
	v_mov_b64 v[24:25], 0
	v_mov_b64 v[126:127], 0
	v_mov_b64 v[128:129], 0
	v_mov_b64 v[30:31], 0
	v_mov_b64 v[32:33], 0
	v_mov_b64 v[34:35], 0
	v_mov_b64 v[36:37], 0
	v_mov_b64 v[130:131], 0
	v_mov_b64 v[132:133], 0
	v_mov_b64 v[42:43], 0
	v_mov_b64 v[44:45], 0
	v_mov_b64 v[74:75], 0
	v_mov_b64 v[76:77], 0
	v_mov_b64 v[50:51], 0
	v_mov_b64 v[52:53], 0
	v_mov_b64 v[106:107], 0
	v_mov_b64 v[108:109], 0
	v_mov_b64 v[90:91], 0
	v_mov_b64 v[92:93], 0
	v_mov_b64 v[138:139], 0
	v_mov_b64 v[140:141], 0
	v_mov_b64 v[134:135], 0
	v_mov_b64 v[136:137], 0
	v_mov_b64 v[38:39], 0
	v_mov_b64 v[40:41], 0
	v_mov_b64 v[78:79], 0
	v_mov_b64 v[80:81], 0
	v_mov_b64 v[46:47], 0
	v_mov_b64 v[48:49], 0
	v_mov_b64 v[110:111], 0
	v_mov_b64 v[112:113], 0
	v_mov_b64 v[62:63], 0
	v_mov_b64 v[64:65], 0
	v_mov_b64 v[142:143], 0
	v_mov_b64 v[144:145], 0
	v_mov_b64 v[102:103], 0
	v_mov_b64 v[104:105], 0

.LBB0_1271:
	s_or_b64 exec, exec, s[6:7]
	v_lshlrev_b32_e32 v126, 2, v177
	s_and_saveexec_b64 s[6:7], s[8:9]
	v_add_u32_e32 v128, s57, v185
	v_add3_u32 v127, v128, v127, v126
	ds_write_b128 v127, v[118:121]
	s_or_b64 exec, exec, s[6:7]
	s_waitcnt lgkmcnt(0)
	v_xor_b32_e32 v118, 0x400, v185
	v_add_u32_e32 v119, s57, v118
	v_cmp_eq_u32_e32 vcc, 0, v1
	v_cmp_ne_u32_e64 s[6:7], 0, v1
	v_mov_b32_e32 v118, 0
	v_mov_b32_e32 v120, 64
	v_lshl_add_u32 v177, v177, 2, v119
	v_mov_b32_e32 v121, v119
	v_mov_b64 v[142:143], 0
	v_mov_b64 v[144:145], 0
	s_barrier
	s_and_saveexec_b64 s[8:9], s[6:7]
	ds_read_b128 v[142:145], v177 offset:64
	v_add_u32_e32 v121, 0x80, v119
	v_mov_b32_e32 v120, 0xc0
	s_or_b64 exec, exec, s[8:9]
	v_add_u32_e32 v121, v121, v126
	v_add3_u32 v119, v119, v120, v126
	ds_read_b128 v[134:137], v121
	ds_read_b128 v[126:129], v119
	v_mov_b32_e32 v119, 0
	v_mov_b64 v[120:121], 0
	s_and_saveexec_b64 s[6:7], vcc
	ds_read_b128 v[118:121], v177 offset:128
	s_or_b64 exec, exec, s[6:7]
	v_mul_f32_e32 v177, 0xbfb8aa3b, v90
	v_exp_f32_e32 v177, v177
	v_mul_f32_e32 v190, 0xbfb8aa3b, v91
	v_exp_f32_e32 v191, v190
	v_mul_f32_e32 v192, 0xbfb8aa3b, v93
	v_add_f32_e32 v177, 1.0, v177
	v_rcp_f32_e32 v194, v177
	v_add_f32_e32 v177, 1.0, v191
	v_mul_f32_e32 v191, 0xbfb8aa3b, v92
	v_exp_f32_e32 v191, v191
	v_exp_f32_e32 v192, v192
	v_rcp_f32_e32 v195, v177
	v_pk_mul_f32 v[108:109], v[108:109], v[112:113]
	v_add_f32_e32 v177, 1.0, v191
	v_rcp_f32_e32 v196, v177
	v_add_f32_e32 v177, 1.0, v192
	v_rcp_f32_e32 v197, v177
	v_pk_mul_f32 v[106:107], v[106:107], v[110:111]
	v_cmp_gt_i32_e64 s[8:9], 2, v176
	v_pk_mul_f32 v[90:91], v[90:91], v[194:195]
	v_pk_mul_f32 v[92:93], v[92:93], v[196:197]
	v_cmp_eq_u32_e64 s[6:7], 0, v176
	s_mul_hi_i32 s49, s20, 6
	s_mul_i32 s48, s20, 6
	v_mov_b32_dpp v113, v138 row_ror:1 row_mask:0xf bank_mask:0xf bound_ctrl:1
	v_mov_b32_dpp v110, v138 row_ror:15 row_mask:0xf bank_mask:0xf bound_ctrl:1
	v_mov_b32_dpp v187, v139 row_ror:1 row_mask:0xf bank_mask:0xf bound_ctrl:1
	v_mov_b32_dpp v112, v139 row_ror:15 row_mask:0xf bank_mask:0xf bound_ctrl:1
	v_mov_b32_dpp v186, v140 row_ror:1 row_mask:0xf bank_mask:0xf bound_ctrl:1
	v_mov_b32_dpp v111, v140 row_ror:15 row_mask:0xf bank_mask:0xf bound_ctrl:1
	v_mov_b32_dpp v189, v141 row_ror:1 row_mask:0xf bank_mask:0xf bound_ctrl:1
	v_mov_b32_dpp v185, v141 row_ror:15 row_mask:0xf bank_mask:0xf bound_ctrl:1
	v_mov_b32_dpp v188, v106 row_ror:15 row_mask:0xf bank_mask:0xf bound_ctrl:1
	v_mov_b32_dpp v190, v107 row_ror:15 row_mask:0xf bank_mask:0xf bound_ctrl:1
	v_mov_b32_dpp v191, v108 row_ror:15 row_mask:0xf bank_mask:0xf bound_ctrl:1
	v_mov_b32_dpp v192, v109 row_ror:15 row_mask:0xf bank_mask:0xf bound_ctrl:1
	v_pk_mul_f32 v[92:93], v[104:105], v[92:93]
	v_pk_mul_f32 v[90:91], v[102:103], v[90:91]
	s_and_b64 s[10:11], vcc, s[8:9]
	s_and_saveexec_b64 s[8:9], s[10:11]
	s_cbranch_execz .LBB0_1280
	v_ashrrev_i32_e32 v177, 31, v176
	v_lshl_add_u64 v[102:103], s[48:49], 0, v[176:177]
	v_lshlrev_b64 v[102:103], 13, v[102:103]
	v_lshl_add_u64 v[102:103], v[158:159], 0, v[102:103]
	v_lshl_add_u64 v[102:103], v[174:175], 2, v[102:103]
	global_store_dwordx4 v[102:103], v[138:141], off
	s_and_b64 exec, exec, s[6:7]
	s_cbranch_execz .LBB0_1280
	v_add_co_u32_e32 v102, vcc, 0x8000, v102
	s_nop 1
	v_addc_co_u32_e32 v103, vcc, 0, v103, vcc
	global_store_dwordx4 v[102:103], v[90:93], off

.LBB0_1382:
	s_ashr_i32 s35, s34, 31
	s_lshl_b64 s[42:43], s[34:35], 20
	s_ashr_i32 s37, s36, 31
	s_ashr_i32 s31, s30, 31
	v_lshl_add_u64 v[0:1], v[168:169], 0, s[42:43]
	s_lshl_b64 s[42:43], s[36:37], 7
	s_lshl_b64 s[44:45], s[30:31], 20
	v_lshl_add_u64 v[182:183], v[0:1], 0, s[42:43]
	v_lshl_add_u64 v[0:1], v[160:161], 0, s[44:45]
	v_lshl_add_u64 v[184:185], v[0:1], 0, s[42:43]
	v_mov_b32_e32 v64, 0
	v_cndmask_b32_e64 v129, v5, v183, s[38:39]
	v_cndmask_b32_e64 v128, v4, v182, s[38:39]
	v_cndmask_b32_e64 v131, v3, v185, s[38:39]
	v_cndmask_b32_e64 v130, v2, v184, s[38:39]
	s_add_i32 s31, s5, -2
	v_lshl_add_u64 v[132:133], v[4:5], 0, s[18:19]
	v_lshl_add_u64 v[134:135], v[2:3], 0, s[24:25]
	s_mov_b32 s35, 0
	v_mov_b32_e32 v65, v64
	v_mov_b64 v[66:67], 0
	v_mov_b64 v[68:69], 0
	v_mov_b64 v[70:71], 0
	v_mov_b64 v[72:73], 0
	v_mov_b64 v[74:75], 0
	v_mov_b64 v[76:77], 0
	v_mov_b64 v[78:79], 0
	v_mov_b64 v[80:81], 0
	v_mov_b64 v[82:83], 0
	v_mov_b64 v[84:85], 0
	v_mov_b64 v[86:87], 0
	v_mov_b64 v[88:89], 0
	v_mov_b64 v[90:91], 0
	v_mov_b64 v[92:93], 0
	v_mov_b64 v[94:95], 0
	v_mov_b64 v[96:97], 0
	v_mov_b64 v[98:99], 0
	v_mov_b64 v[100:101], 0
	v_mov_b64 v[102:103], 0
	v_mov_b64 v[104:105], 0
	v_mov_b64 v[106:107], 0
	v_mov_b64 v[108:109], 0
	v_mov_b64 v[110:111], 0
	v_mov_b64 v[112:113], 0
	v_mov_b64 v[114:115], 0
	v_mov_b64 v[116:117], 0
	v_mov_b64 v[118:119], 0
	v_mov_b64 v[120:121], 0
	v_mov_b64 v[122:123], 0
	v_mov_b64 v[124:125], 0
	v_mov_b64 v[126:127], 0
	v_mov_b64 v[0:1], 0
	v_mov_b64 v[2:3], 0
	v_mov_b64 v[4:5], 0
	v_mov_b64 v[6:7], 0
	v_mov_b64 v[8:9], 0
	v_mov_b64 v[10:11], 0
	v_mov_b64 v[12:13], 0
	v_mov_b64 v[14:15], 0
	v_mov_b64 v[16:17], 0
	v_mov_b64 v[18:19], 0
	v_mov_b64 v[20:21], 0
	v_mov_b64 v[22:23], 0
	v_mov_b64 v[24:25], 0
	v_mov_b64 v[26:27], 0
	v_mov_b64 v[28:29], 0
	v_mov_b64 v[30:31], 0
	v_mov_b64 v[32:33], 0
	v_mov_b64 v[34:35], 0
	v_mov_b64 v[36:37], 0
	v_mov_b64 v[38:39], 0
	v_mov_b64 v[40:41], 0
	v_mov_b64 v[42:43], 0
	v_mov_b64 v[44:45], 0
	v_mov_b64 v[46:47], 0
	v_mov_b64 v[48:49], 0
	v_mov_b64 v[50:51], 0
	v_mov_b64 v[52:53], 0
	v_mov_b64 v[54:55], 0
	v_mov_b64 v[56:57], 0
	v_mov_b64 v[58:59], 0
	v_mov_b64 v[60:61], 0
	v_mov_b64 v[62:63], 0
